# LN phase part 1: the four pieces of each row loaded together with real loads (replaces the dummy prefetch), instances k8/k11
# speedup vs baseline: 1.0298x; 1.0060x over previous
.LBB0_51:
	global_load_dwordx4 v[154:157], v[74:75], off
	global_load_dwordx4 v[158:161], v[76:77], off
	global_load_dwordx4 v[162:165], v[74:75], off offset:1024
	global_load_dwordx4 v[166:169], v[76:77], off offset:1024
	global_load_dwordx4 v[170:173], v[74:75], off offset:2048
	global_load_dwordx4 v[174:177], v[76:77], off offset:2048
	global_load_dwordx4 v[178:181], v[74:75], off offset:3072
	global_load_dwordx4 v[182:185], v[76:77], off offset:3072
	v_add_u32_e32 v0, 0xfffff000, v64
	v_ashrrev_i32_e32 v0, 10, v0
	v_add_u32_e32 v0, 1, v0
	v_cmp_lt_i32_e32 vcc, s33, v64
	s_mov_b32 s2, 0x1000000
	global_load_dwordx4 v[186:189], v[86:87], off offset:1024
	global_load_dwordx4 v[190:193], v[86:87], off offset:2048
	global_load_dwordx4 v[194:197], v[86:87], off offset:3072
	flat_load_dwordx4 v[8:11], v[86:87]
	v_cndmask_b32_e32 v4, 0, v0, vcc
	v_add_u32_e32 v0, s38, v64
	v_cmp_lt_i32_e32 vcc, s6, v0
	v_ashrrev_i32_e32 v5, 31, v4
	v_lshl_add_u64 v[88:89], v[4:5], 0, s[28:29]
	v_cndmask_b32_e32 v0, v0, v64, vcc
	v_add_u32_e32 v1, 0xfffff000, v0
	v_ashrrev_i32_e32 v1, 10, v1
	v_add_u32_e32 v1, 1, v1
	v_cmp_lt_i32_e32 vcc, s33, v0
	v_mad_u64_u32 v[4:5], s[4:5], v88, s7, v[78:79]
	s_nop 0
	v_cndmask_b32_e32 v2, 0, v1, vcc
	v_add_u32_e32 v1, s35, v64
	v_cmp_lt_i32_e32 vcc, s6, v1
	v_mad_i32_i24 v5, v89, s7, v5
	global_load_dwordx4 v[198:201], v[4:5], off offset:1024
	global_load_dwordx4 v[202:205], v[4:5], off offset:2048
	global_load_dwordx4 v[224:227], v[4:5], off offset:3072
	flat_load_dwordx4 v[12:15], v[4:5]
	v_cndmask_b32_e32 v40, v1, v64, vcc
	v_add_u32_e32 v1, 0xfffff000, v40
	v_ashrrev_i32_e32 v1, 10, v1
	v_add_u32_e32 v1, 1, v1
	v_cmp_lt_i32_e32 vcc, s33, v40
	v_ashrrev_i32_e32 v3, 31, v2
	v_lshl_add_u64 v[92:93], v[2:3], 0, s[28:29]
	v_cndmask_b32_e32 v42, 0, v1, vcc
	v_add_u32_e32 v1, s26, v64
	v_cmp_lt_i32_e32 vcc, s6, v1
	s_mov_b64 s[8:9], 0x1000000
	v_mad_u64_u32 v[48:49], s[4:5], v92, s7, v[78:79]
	v_cndmask_b32_e32 v20, v1, v64, vcc
	v_add_u32_e32 v1, 0xfffff000, v20
	v_ashrrev_i32_e32 v1, 10, v1
	v_add_u32_e32 v1, 1, v1
	v_cmp_lt_i32_e32 vcc, s33, v20
	v_lshlrev_b32_e32 v152, 1, v66
	v_mad_i32_i24 v49, v93, s7, v49
	v_cndmask_b32_e32 v22, 0, v1, vcc
	v_add_co_u32_e32 v6, vcc, s2, v84
	s_brev_b32 s2, 64
	s_nop 0
	v_addc_co_u32_e32 v7, vcc, 0, v85, vcc
	v_add_co_u32_e32 v24, vcc, s2, v84
	global_load_dwordx2 v[228:229], v[6:7], off offset:512
	global_load_dwordx2 v[230:231], v[6:7], off offset:1024
	global_load_dwordx2 v[232:233], v[6:7], off offset:1536
	flat_load_dwordx2 v[16:17], v[6:7]
	s_nop 0
	v_addc_co_u32_e32 v25, vcc, 0, v85, vcc
	global_load_dwordx2 v[234:235], v[24:25], off offset:512
	global_load_dwordx2 v[236:237], v[24:25], off offset:1024
	global_load_dwordx2 v[238:239], v[24:25], off offset:1536
	flat_load_dwordx2 v[26:27], v[24:25]
	v_lshlrev_b32_e32 v104, 1, v68
	v_mov_b32_e32 v105, v153
	v_lshlrev_b32_e32 v106, 1, v70
	v_mov_b32_e32 v107, v153
	v_lshlrev_b32_e32 v120, 1, v72
	v_mov_b32_e32 v121, v153
	v_ashrrev_i32_e32 v41, 31, v40
	v_ashrrev_i32_e32 v43, 31, v42
	v_lshlrev_b64 v[96:97], 11, v[40:41]
	v_lshl_add_u64 v[98:99], v[42:43], 0, s[28:29]
	v_lshl_add_u64 v[42:43], s[56:57], 0, v[96:97]
	v_ashrrev_i32_e32 v21, 31, v20
	v_ashrrev_i32_e32 v23, 31, v22
	s_mov_b32 s2, 0x3727c5ac
	s_waitcnt vmcnt(0) lgkmcnt(0)
	v_lshlrev_b32_e32 v18, 16, v16
	v_and_b32_e32 v19, 0xffff0000, v16
	v_lshlrev_b32_e32 v16, 16, v17
	v_and_b32_e32 v17, 0xffff0000, v17
	v_lshlrev_b32_e32 v28, 16, v26
	v_and_b32_e32 v29, 0xffff0000, v26
	v_lshlrev_b32_e32 v26, 16, v27
	v_and_b32_e32 v27, 0xffff0000, v27
	v_pk_add_f32 v[18:19], v[18:19], v[28:29]
	v_pk_add_f32 v[16:17], v[16:17], v[26:27]
	v_pk_mul_f32 v[12:13], v[12:13], v[18:19]
	v_pk_mul_f32 v[14:15], v[14:15], v[16:17]
	v_pk_fma_f32 v[8:9], v[8:9], s[42:43], v[12:13] op_sel_hi:[1,0,1]
	v_pk_fma_f32 v[10:11], v[10:11], s[42:43], v[14:15] op_sel_hi:[1,0,1]
	v_mov_b32_e32 v14, v8
	v_pk_mov_b32 v[12:13], v[8:9], v[10:11] op_sel:[1,0]
	v_mov_b32_e32 v15, v11
	v_pk_add_f32 v[12:13], v[12:13], v[14:15]
	s_nop 0
	v_add_f32_e32 v1, v12, v13
	v_mov_b64_e32 v[12:13], v[186:187]
	v_mov_b64_e32 v[14:15], v[188:189]
	v_mov_b64_e32 v[16:17], v[198:199]
	v_mov_b64_e32 v[18:19], v[200:201]
	v_mov_b64_e32 v[26:27], v[228:229]
	v_mov_b64_e32 v[32:33], v[234:235]
	v_add_f32_e32 v28, 0, v1
	v_ashrrev_i32_e32 v1, 31, v0
	v_lshlrev_b64 v[90:91], 11, v[0:1]
	v_lshlrev_b64 v[2:3], 12, v[0:1]
	v_lshlrev_b32_e32 v30, 16, v26
	v_and_b32_e32 v31, 0xffff0000, v26
	v_lshlrev_b32_e32 v26, 16, v27
	v_and_b32_e32 v27, 0xffff0000, v27
	v_lshlrev_b32_e32 v34, 16, v32
	v_and_b32_e32 v35, 0xffff0000, v32
	v_lshlrev_b32_e32 v32, 16, v33
	v_and_b32_e32 v33, 0xffff0000, v33
	v_pk_add_f32 v[30:31], v[30:31], v[34:35]
	v_pk_add_f32 v[26:27], v[26:27], v[32:33]
	v_pk_mul_f32 v[16:17], v[16:17], v[30:31]
	v_pk_mul_f32 v[18:19], v[18:19], v[26:27]
	v_pk_fma_f32 v[12:13], v[12:13], s[42:43], v[16:17] op_sel_hi:[1,0,1]
	v_pk_fma_f32 v[14:15], v[14:15], s[42:43], v[18:19] op_sel_hi:[1,0,1]
	v_mov_b32_e32 v18, v12
	v_pk_mov_b32 v[16:17], v[12:13], v[14:15] op_sel:[1,0]
	v_mov_b32_e32 v19, v15
	v_pk_add_f32 v[16:17], v[16:17], v[18:19]
	s_nop 0
	v_pk_add_f32 v[30:31], v[16:17], v[16:17] op_sel:[0,1] op_sel_hi:[1,0]
	v_mov_b64_e32 v[16:17], v[190:191]
	v_mov_b64_e32 v[18:19], v[192:193]
	v_mov_b64_e32 v[32:33], v[202:203]
	v_mov_b64_e32 v[34:35], v[204:205]
	v_mov_b64_e32 v[26:27], v[230:231]
	v_mov_b64_e32 v[38:39], v[236:237]
	v_lshlrev_b32_e32 v36, 16, v26
	v_and_b32_e32 v37, 0xffff0000, v26
	v_lshlrev_b32_e32 v44, 16, v38
	v_and_b32_e32 v45, 0xffff0000, v38
	v_lshlrev_b32_e32 v26, 16, v27
	v_and_b32_e32 v27, 0xffff0000, v27
	v_lshlrev_b32_e32 v38, 16, v39
	v_and_b32_e32 v39, 0xffff0000, v39
	v_pk_add_f32 v[36:37], v[36:37], v[44:45]
	v_pk_add_f32 v[26:27], v[26:27], v[38:39]
	v_pk_mul_f32 v[32:33], v[32:33], v[36:37]
	v_pk_mul_f32 v[26:27], v[34:35], v[26:27]
	v_pk_fma_f32 v[16:17], v[16:17], s[42:43], v[32:33] op_sel_hi:[1,0,1]
	v_mov_b64_e32 v[32:33], v[194:195]
	v_mov_b64_e32 v[34:35], v[196:197]
	v_mov_b64_e32 v[36:37], v[224:225]
	v_mov_b64_e32 v[38:39], v[226:227]
	s_nop 0
	v_mov_b64_e32 v[4:5], v[232:233]
	v_pk_fma_f32 v[18:19], v[18:19], s[42:43], v[26:27] op_sel_hi:[1,0,1]
	v_mov_b64_e32 v[24:25], v[238:239]
	v_add_f32_e32 v44, v16, v17
	v_add_f32_e32 v46, v18, v19
	v_lshlrev_b32_e32 v6, 16, v4
	v_and_b32_e32 v7, 0xffff0000, v4
	v_lshlrev_b32_e32 v26, 16, v24
	v_and_b32_e32 v27, 0xffff0000, v24
	v_lshlrev_b32_e32 v4, 16, v5
	v_and_b32_e32 v5, 0xffff0000, v5
	v_lshlrev_b32_e32 v24, 16, v25
	v_and_b32_e32 v25, 0xffff0000, v25
	v_pk_add_f32 v[6:7], v[6:7], v[26:27]
	v_pk_add_f32 v[4:5], v[4:5], v[24:25]
	v_pk_mul_f32 v[6:7], v[36:37], v[6:7]
	v_pk_mul_f32 v[4:5], v[38:39], v[4:5]
	v_pk_fma_f32 v[24:25], v[32:33], s[42:43], v[6:7] op_sel_hi:[1,0,1]
	v_pk_fma_f32 v[26:27], v[34:35], s[42:43], v[4:5] op_sel_hi:[1,0,1]
	v_mov_b32_e32 v29, v24
	v_mov_b32_e32 v31, v25
	v_pk_add_f32 v[4:5], v[28:29], v[30:31]
	v_mov_b32_e32 v45, v26
	v_mov_b32_e32 v47, v27
	v_lshl_add_u64 v[28:29], s[56:57], 0, v[90:91]
	v_pk_add_f32 v[6:7], v[44:45], v[46:47]
	v_lshl_add_u64 v[44:45], v[28:29], 0, s[8:9]
	v_pk_add_f32 v[4:5], v[4:5], v[6:7]
	v_lshl_add_u64 v[52:53], v[28:29], 0, v[152:153]
	v_lshl_add_u64 v[34:35], v[44:45], 0, v[152:153]
	v_add_f32_e32 v122, v4, v5
	global_load_dwordx4 v[186:189], v[48:49], off offset:1024
	global_load_dwordx4 v[190:193], v[48:49], off offset:2048
	global_load_dwordx4 v[194:197], v[48:49], off offset:3072
	flat_load_dwordx4 v[4:7], v[48:49]
	global_load_dwordx2 v[228:229], v[52:53], off offset:512
	global_load_dwordx2 v[230:231], v[52:53], off offset:1024
	global_load_dwordx2 v[232:233], v[52:53], off offset:1536
	flat_load_dwordx2 v[28:29], v[52:53]
	v_lshl_add_u64 v[32:33], v[80:81], 0, v[2:3]
	global_load_dwordx2 v[234:235], v[34:35], off offset:512
	global_load_dwordx2 v[236:237], v[34:35], off offset:1024
	global_load_dwordx2 v[238:239], v[34:35], off offset:1536
	flat_load_dwordx2 v[34:35], v[34:35]
	v_lshl_add_u64 v[38:39], v[44:45], 0, v[104:105]
	global_load_dwordx4 v[198:201], v[32:33], off offset:1024
	global_load_dwordx4 v[202:205], v[32:33], off offset:2048
	global_load_dwordx4 v[224:227], v[32:33], off offset:3072
	flat_load_dwordx4 v[0:3], v[32:33]
	v_lshl_add_u64 v[54:55], v[44:45], 0, v[106:107]
	v_lshl_add_u64 v[44:45], v[44:45], 0, v[120:121]
	s_waitcnt vmcnt(0) lgkmcnt(0)
	v_lshlrev_b32_e32 v30, 16, v28
	v_and_b32_e32 v31, 0xffff0000, v28
	v_lshlrev_b32_e32 v28, 16, v29
	v_and_b32_e32 v29, 0xffff0000, v29
	v_lshlrev_b32_e32 v36, 16, v34
	v_and_b32_e32 v37, 0xffff0000, v34
	v_lshlrev_b32_e32 v34, 16, v35
	v_and_b32_e32 v35, 0xffff0000, v35
	v_pk_add_f32 v[30:31], v[30:31], v[36:37]
	v_pk_add_f32 v[28:29], v[28:29], v[34:35]
	v_pk_mul_f32 v[4:5], v[4:5], v[30:31]
	v_pk_mul_f32 v[6:7], v[6:7], v[28:29]
	v_pk_fma_f32 v[28:29], v[0:1], s[42:43], v[4:5] op_sel_hi:[1,0,1]
	v_pk_fma_f32 v[30:31], v[2:3], s[42:43], v[6:7] op_sel_hi:[1,0,1]
	v_mov_b32_e32 v2, v28
	v_pk_mov_b32 v[0:1], v[28:29], v[30:31] op_sel:[1,0]
	v_mov_b32_e32 v3, v31
	v_pk_add_f32 v[0:1], v[0:1], v[2:3]
	s_nop 0
	v_add_f32_e32 v0, v0, v1
	v_add_f32_e32 v46, 0, v0
	v_mov_b64_e32 v[0:1], v[198:199]
	v_mov_b64_e32 v[2:3], v[200:201]
	v_mov_b64_e32 v[4:5], v[186:187]
	v_mov_b64_e32 v[6:7], v[188:189]
	v_mov_b64_e32 v[34:35], v[228:229]
	v_lshlrev_b32_e32 v36, 16, v34
	v_mov_b64_e32 v[38:39], v[234:235]
	v_and_b32_e32 v37, 0xffff0000, v34
	v_lshlrev_b32_e32 v34, 16, v35
	v_and_b32_e32 v35, 0xffff0000, v35
	v_lshlrev_b32_e32 v50, 16, v38
	v_and_b32_e32 v51, 0xffff0000, v38
	v_lshlrev_b32_e32 v38, 16, v39
	v_and_b32_e32 v39, 0xffff0000, v39
	v_pk_add_f32 v[36:37], v[36:37], v[50:51]
	v_pk_add_f32 v[34:35], v[34:35], v[38:39]
	v_pk_mul_f32 v[4:5], v[4:5], v[36:37]
	v_pk_mul_f32 v[6:7], v[6:7], v[34:35]
	v_pk_fma_f32 v[38:39], v[0:1], s[42:43], v[4:5] op_sel_hi:[1,0,1]
	v_pk_fma_f32 v[60:61], v[2:3], s[42:43], v[6:7] op_sel_hi:[1,0,1]
	v_mov_b32_e32 v2, v38
	v_pk_mov_b32 v[0:1], v[38:39], v[60:61] op_sel:[1,0]
	v_mov_b32_e32 v3, v61
	v_pk_add_f32 v[0:1], v[0:1], v[2:3]
	s_nop 0
	v_pk_add_f32 v[50:51], v[0:1], v[0:1] op_sel:[0,1] op_sel_hi:[1,0]
	v_mov_b64_e32 v[0:1], v[202:203]
	v_mov_b64_e32 v[2:3], v[204:205]
	v_mov_b64_e32 v[4:5], v[190:191]
	v_mov_b64_e32 v[6:7], v[192:193]
	v_mov_b64_e32 v[34:35], v[230:231]
	v_lshlrev_b32_e32 v36, 16, v34
	v_mov_b64_e32 v[54:55], v[236:237]
	v_and_b32_e32 v37, 0xffff0000, v34
	v_lshlrev_b32_e32 v34, 16, v35
	v_and_b32_e32 v35, 0xffff0000, v35
	v_lshlrev_b32_e32 v56, 16, v54
	v_and_b32_e32 v57, 0xffff0000, v54
	v_lshlrev_b32_e32 v54, 16, v55
	v_and_b32_e32 v55, 0xffff0000, v55
	v_pk_add_f32 v[34:35], v[34:35], v[54:55]
	v_pk_add_f32 v[36:37], v[36:37], v[56:57]
	v_pk_mul_f32 v[6:7], v[6:7], v[34:35]
	v_pk_mul_f32 v[4:5], v[4:5], v[36:37]
	v_pk_fma_f32 v[36:37], v[2:3], s[42:43], v[6:7] op_sel_hi:[1,0,1]
	v_pk_fma_f32 v[34:35], v[0:1], s[42:43], v[4:5] op_sel_hi:[1,0,1]
	v_mov_b64_e32 v[0:1], v[224:225]
	v_mov_b64_e32 v[2:3], v[226:227]
	v_mov_b64_e32 v[4:5], v[194:195]
	v_mov_b64_e32 v[6:7], v[196:197]
	s_nop 0
	v_mov_b64_e32 v[52:53], v[232:233]
	v_add_f32_e32 v54, v34, v35
	v_mov_b64_e32 v[44:45], v[238:239]
	v_add_f32_e32 v56, v36, v37
	v_lshlrev_b32_e32 v48, 16, v52
	v_and_b32_e32 v49, 0xffff0000, v52
	v_lshlrev_b32_e32 v58, 16, v44
	v_and_b32_e32 v59, 0xffff0000, v44
	v_lshlrev_b32_e32 v52, 16, v53
	v_and_b32_e32 v53, 0xffff0000, v53
	v_lshlrev_b32_e32 v44, 16, v45
	v_and_b32_e32 v45, 0xffff0000, v45
	v_pk_add_f32 v[48:49], v[48:49], v[58:59]
	v_pk_add_f32 v[44:45], v[52:53], v[44:45]
	v_pk_mul_f32 v[4:5], v[4:5], v[48:49]
	v_pk_mul_f32 v[6:7], v[6:7], v[44:45]
	v_pk_fma_f32 v[62:63], v[0:1], s[42:43], v[4:5] op_sel_hi:[1,0,1]
	v_pk_fma_f32 v[118:119], v[2:3], s[42:43], v[6:7] op_sel_hi:[1,0,1]
	v_mov_b32_e32 v47, v62
	v_mov_b32_e32 v51, v63
	v_pk_add_f32 v[0:1], v[46:47], v[50:51]
	v_mov_b32_e32 v55, v118
	v_mov_b32_e32 v57, v119
	v_lshl_add_u64 v[44:45], v[42:43], 0, s[8:9]
	v_mad_u64_u32 v[46:47], s[4:5], v98, s7, v[78:79]
	v_pk_add_f32 v[2:3], v[54:55], v[56:57]
	v_mad_i32_i24 v47, v99, s7, v47
	v_lshl_add_u64 v[42:43], v[42:43], 0, v[152:153]
	v_lshl_add_u64 v[52:53], v[44:45], 0, v[152:153]
	v_pk_add_f32 v[0:1], v[0:1], v[2:3]
	global_load_dwordx4 v[186:189], v[46:47], off offset:1024
	global_load_dwordx4 v[190:193], v[46:47], off offset:2048
	global_load_dwordx4 v[194:197], v[46:47], off offset:3072
	flat_load_dwordx4 v[4:7], v[46:47]
	global_load_dwordx2 v[228:229], v[42:43], off offset:512
	global_load_dwordx2 v[230:231], v[42:43], off offset:1024
	global_load_dwordx2 v[232:233], v[42:43], off offset:1536
	flat_load_dwordx2 v[48:49], v[42:43]
	v_add_f32_e32 v126, v0, v1
	global_load_dwordx2 v[234:235], v[52:53], off offset:512
	global_load_dwordx2 v[236:237], v[52:53], off offset:1024
	global_load_dwordx2 v[238:239], v[52:53], off offset:1536
	flat_load_dwordx2 v[52:53], v[52:53]
	v_lshlrev_b64 v[0:1], 12, v[40:41]
	v_lshl_add_u64 v[40:41], v[80:81], 0, v[0:1]
	global_load_dwordx4 v[198:201], v[40:41], off offset:1024
	global_load_dwordx4 v[202:205], v[40:41], off offset:2048
	global_load_dwordx4 v[224:227], v[40:41], off offset:3072
	flat_load_dwordx4 v[0:3], v[40:41]
	v_lshl_add_u64 v[56:57], v[44:45], 0, v[104:105]
	v_lshl_add_u64 v[102:103], v[44:45], 0, v[106:107]
	v_lshl_add_u64 v[44:45], v[44:45], 0, v[120:121]
	s_waitcnt vmcnt(0) lgkmcnt(0)
	v_lshlrev_b32_e32 v50, 16, v48
	v_and_b32_e32 v51, 0xffff0000, v48
	v_lshlrev_b32_e32 v48, 16, v49
	v_and_b32_e32 v49, 0xffff0000, v49
	v_lshlrev_b32_e32 v54, 16, v52
	v_and_b32_e32 v55, 0xffff0000, v52
	v_lshlrev_b32_e32 v52, 16, v53
	v_and_b32_e32 v53, 0xffff0000, v53
	v_pk_add_f32 v[50:51], v[50:51], v[54:55]
	v_pk_add_f32 v[48:49], v[48:49], v[52:53]
	v_pk_mul_f32 v[4:5], v[4:5], v[50:51]
	v_pk_mul_f32 v[6:7], v[6:7], v[48:49]
	v_pk_fma_f32 v[50:51], v[0:1], s[42:43], v[4:5] op_sel_hi:[1,0,1]
	v_pk_fma_f32 v[52:53], v[2:3], s[42:43], v[6:7] op_sel_hi:[1,0,1]
	v_mov_b32_e32 v2, v50
	v_pk_mov_b32 v[0:1], v[50:51], v[52:53] op_sel:[1,0]
	v_mov_b32_e32 v3, v53
	v_pk_add_f32 v[0:1], v[0:1], v[2:3]
	s_nop 0
	v_add_f32_e32 v0, v0, v1
	v_add_f32_e32 v94, 0, v0
	v_mov_b64_e32 v[0:1], v[198:199]
	v_mov_b64_e32 v[2:3], v[200:201]
	v_mov_b64_e32 v[4:5], v[186:187]
	v_mov_b64_e32 v[6:7], v[188:189]
	v_mov_b64_e32 v[48:49], v[228:229]
	v_lshlrev_b32_e32 v54, 16, v48
	v_mov_b64_e32 v[56:57], v[234:235]
	v_and_b32_e32 v55, 0xffff0000, v48
	v_lshlrev_b32_e32 v48, 16, v49
	v_and_b32_e32 v49, 0xffff0000, v49
	v_lshlrev_b32_e32 v58, 16, v56
	v_and_b32_e32 v59, 0xffff0000, v56
	v_lshlrev_b32_e32 v56, 16, v57
	v_and_b32_e32 v57, 0xffff0000, v57
	v_pk_add_f32 v[54:55], v[54:55], v[58:59]
	v_pk_add_f32 v[48:49], v[48:49], v[56:57]
	v_pk_mul_f32 v[4:5], v[4:5], v[54:55]
	v_pk_mul_f32 v[6:7], v[6:7], v[48:49]
	v_pk_fma_f32 v[56:57], v[0:1], s[42:43], v[4:5] op_sel_hi:[1,0,1]
	v_pk_fma_f32 v[58:59], v[2:3], s[42:43], v[6:7] op_sel_hi:[1,0,1]
	v_mov_b32_e32 v2, v56
	v_pk_mov_b32 v[0:1], v[56:57], v[58:59] op_sel:[1,0]
	v_mov_b32_e32 v3, v59
	v_pk_add_f32 v[0:1], v[0:1], v[2:3]
	s_nop 0
	v_pk_add_f32 v[100:101], v[0:1], v[0:1] op_sel:[0,1] op_sel_hi:[1,0]
	v_mov_b64_e32 v[0:1], v[202:203]
	v_mov_b64_e32 v[2:3], v[204:205]
	v_mov_b64_e32 v[4:5], v[190:191]
	v_mov_b64_e32 v[6:7], v[192:193]
	v_mov_b64_e32 v[48:49], v[230:231]
	v_lshlrev_b32_e32 v54, 16, v48
	v_mov_b64_e32 v[102:103], v[236:237]
	v_and_b32_e32 v55, 0xffff0000, v48
	v_lshlrev_b32_e32 v48, 16, v49
	v_and_b32_e32 v49, 0xffff0000, v49
	v_lshlrev_b32_e32 v108, 16, v102
	v_and_b32_e32 v109, 0xffff0000, v102
	v_lshlrev_b32_e32 v102, 16, v103
	v_and_b32_e32 v103, 0xffff0000, v103
	v_pk_add_f32 v[48:49], v[48:49], v[102:103]
	v_pk_add_f32 v[54:55], v[54:55], v[108:109]
	v_pk_mul_f32 v[6:7], v[6:7], v[48:49]
	v_pk_mul_f32 v[4:5], v[4:5], v[54:55]
	v_pk_fma_f32 v[116:117], v[2:3], s[42:43], v[6:7] op_sel_hi:[1,0,1]
	v_pk_fma_f32 v[54:55], v[0:1], s[42:43], v[4:5] op_sel_hi:[1,0,1]
	v_mov_b64_e32 v[0:1], v[224:225]
	v_mov_b64_e32 v[2:3], v[226:227]
	v_mov_b64_e32 v[4:5], v[194:195]
	v_mov_b64_e32 v[6:7], v[196:197]
	s_nop 0
	v_mov_b64_e32 v[42:43], v[232:233]
	v_add_f32_e32 v102, v54, v55
	v_mov_b64_e32 v[44:45], v[238:239]
	v_add_f32_e32 v108, v116, v117
	v_lshlrev_b32_e32 v46, 16, v42
	v_and_b32_e32 v47, 0xffff0000, v42
	v_lshlrev_b32_e32 v42, 16, v43
	v_and_b32_e32 v43, 0xffff0000, v43
	v_lshlrev_b32_e32 v48, 16, v44
	v_and_b32_e32 v49, 0xffff0000, v44
	v_lshlrev_b32_e32 v44, 16, v45
	v_and_b32_e32 v45, 0xffff0000, v45
	v_pk_add_f32 v[42:43], v[42:43], v[44:45]
	v_pk_add_f32 v[44:45], v[46:47], v[48:49]
	v_pk_mul_f32 v[6:7], v[6:7], v[42:43]
	v_pk_mul_f32 v[4:5], v[4:5], v[44:45]
	v_pk_fma_f32 v[48:49], v[2:3], s[42:43], v[6:7] op_sel_hi:[1,0,1]
	v_pk_fma_f32 v[46:47], v[0:1], s[42:43], v[4:5] op_sel_hi:[1,0,1]
	v_mov_b32_e32 v103, v48
	v_mov_b32_e32 v95, v46
	v_mov_b32_e32 v101, v47
	v_mov_b32_e32 v109, v49
	v_pk_add_f32 v[0:1], v[94:95], v[100:101]
	v_pk_add_f32 v[2:3], v[102:103], v[108:109]
	v_lshlrev_b64 v[94:95], 11, v[20:21]
	v_pk_add_f32 v[0:1], v[0:1], v[2:3]
	v_lshl_add_u64 v[100:101], v[22:23], 0, s[28:29]
	v_add_f32_e32 v125, v0, v1
	v_lshlrev_b64 v[0:1], 12, v[20:21]
	v_lshl_add_u64 v[20:21], s[56:57], 0, v[94:95]
	v_lshl_add_u64 v[22:23], v[20:21], 0, s[8:9]
	v_mad_u64_u32 v[128:129], s[4:5], v100, s7, v[78:79]
	v_mad_i32_i24 v129, v101, s7, v129
	v_lshl_add_u64 v[20:21], v[20:21], 0, v[152:153]
	v_lshl_add_u64 v[108:109], v[22:23], 0, v[152:153]
	global_load_dwordx4 v[186:189], v[128:129], off offset:1024
	global_load_dwordx4 v[190:193], v[128:129], off offset:2048
	global_load_dwordx4 v[194:197], v[128:129], off offset:3072
	flat_load_dwordx4 v[4:7], v[128:129]
	global_load_dwordx2 v[228:229], v[20:21], off offset:512
	global_load_dwordx2 v[230:231], v[20:21], off offset:1024
	global_load_dwordx2 v[232:233], v[20:21], off offset:1536
	flat_load_dwordx2 v[42:43], v[20:21]
	v_lshl_add_u64 v[102:103], v[80:81], 0, v[0:1]
	global_load_dwordx2 v[234:235], v[108:109], off offset:512
	global_load_dwordx2 v[236:237], v[108:109], off offset:1024
	global_load_dwordx2 v[238:239], v[108:109], off offset:1536
	flat_load_dwordx2 v[108:109], v[108:109]
	v_lshl_add_u64 v[104:105], v[22:23], 0, v[104:105]
	global_load_dwordx4 v[198:201], v[102:103], off offset:1024
	global_load_dwordx4 v[202:205], v[102:103], off offset:2048
	global_load_dwordx4 v[224:227], v[102:103], off offset:3072
	flat_load_dwordx4 v[0:3], v[102:103]
	v_lshl_add_u64 v[106:107], v[22:23], 0, v[106:107]
	v_lshl_add_u64 v[22:23], v[22:23], 0, v[120:121]
	v_readlane_b32 s4, v254, 33
	v_readlane_b32 s5, v254, 34
	s_waitcnt vmcnt(0) lgkmcnt(0)
	v_lshlrev_b32_e32 v44, 16, v42
	v_and_b32_e32 v45, 0xffff0000, v42
	v_lshlrev_b32_e32 v42, 16, v43
	v_and_b32_e32 v43, 0xffff0000, v43
	v_lshlrev_b32_e32 v110, 16, v108
	v_and_b32_e32 v111, 0xffff0000, v108
	v_lshlrev_b32_e32 v108, 16, v109
	v_and_b32_e32 v109, 0xffff0000, v109
	v_pk_add_f32 v[44:45], v[44:45], v[110:111]
	v_pk_add_f32 v[42:43], v[42:43], v[108:109]
	v_pk_mul_f32 v[4:5], v[4:5], v[44:45]
	v_pk_mul_f32 v[6:7], v[6:7], v[42:43]
	v_pk_fma_f32 v[44:45], v[0:1], s[42:43], v[4:5] op_sel_hi:[1,0,1]
	v_pk_fma_f32 v[114:115], v[2:3], s[42:43], v[6:7] op_sel_hi:[1,0,1]
	v_mov_b32_e32 v2, v44
	v_pk_mov_b32 v[0:1], v[44:45], v[114:115] op_sel:[1,0]
	v_mov_b32_e32 v3, v115
	v_pk_add_f32 v[0:1], v[0:1], v[2:3]
	s_nop 0
	v_add_f32_e32 v0, v0, v1
	v_add_f32_e32 v130, 0, v0
	v_mov_b64_e32 v[0:1], v[198:199]
	v_mov_b64_e32 v[2:3], v[200:201]
	v_mov_b64_e32 v[4:5], v[186:187]
	v_mov_b64_e32 v[6:7], v[188:189]
	v_mov_b64_e32 v[42:43], v[228:229]
	v_lshlrev_b32_e32 v108, 16, v42
	v_mov_b64_e32 v[104:105], v[234:235]
	v_and_b32_e32 v109, 0xffff0000, v42
	v_lshlrev_b32_e32 v42, 16, v43
	v_and_b32_e32 v43, 0xffff0000, v43
	v_lshlrev_b32_e32 v110, 16, v104
	v_and_b32_e32 v111, 0xffff0000, v104
	v_lshlrev_b32_e32 v104, 16, v105
	v_and_b32_e32 v105, 0xffff0000, v105
	v_pk_add_f32 v[108:109], v[108:109], v[110:111]
	v_pk_add_f32 v[42:43], v[42:43], v[104:105]
	v_pk_mul_f32 v[4:5], v[4:5], v[108:109]
	v_pk_mul_f32 v[6:7], v[6:7], v[42:43]
	v_pk_fma_f32 v[42:43], v[0:1], s[42:43], v[4:5] op_sel_hi:[1,0,1]
	v_pk_fma_f32 v[112:113], v[2:3], s[42:43], v[6:7] op_sel_hi:[1,0,1]
	v_mov_b32_e32 v2, v42
	v_pk_mov_b32 v[0:1], v[42:43], v[112:113] op_sel:[1,0]
	v_mov_b32_e32 v3, v113
	v_pk_add_f32 v[0:1], v[0:1], v[2:3]
	s_nop 0
	v_pk_add_f32 v[132:133], v[0:1], v[0:1] op_sel:[0,1] op_sel_hi:[1,0]
	v_mov_b64_e32 v[0:1], v[202:203]
	v_mov_b64_e32 v[2:3], v[204:205]
	v_mov_b64_e32 v[4:5], v[190:191]
	v_mov_b64_e32 v[6:7], v[192:193]
	v_mov_b64_e32 v[104:105], v[230:231]
	v_lshlrev_b32_e32 v108, 16, v104
	v_mov_b64_e32 v[106:107], v[236:237]
	v_and_b32_e32 v109, 0xffff0000, v104
	v_lshlrev_b32_e32 v104, 16, v105
	v_and_b32_e32 v105, 0xffff0000, v105
	v_lshlrev_b32_e32 v110, 16, v106
	v_and_b32_e32 v111, 0xffff0000, v106
	v_lshlrev_b32_e32 v106, 16, v107
	v_and_b32_e32 v107, 0xffff0000, v107
	v_pk_add_f32 v[104:105], v[104:105], v[106:107]
	v_pk_add_f32 v[106:107], v[108:109], v[110:111]
	v_pk_mul_f32 v[6:7], v[6:7], v[104:105]
	v_pk_mul_f32 v[4:5], v[4:5], v[106:107]
	v_pk_fma_f32 v[110:111], v[2:3], s[42:43], v[6:7] op_sel_hi:[1,0,1]
	v_pk_fma_f32 v[108:109], v[0:1], s[42:43], v[4:5] op_sel_hi:[1,0,1]
	v_mov_b64_e32 v[0:1], v[224:225]
	v_mov_b64_e32 v[2:3], v[226:227]
	v_mov_b64_e32 v[4:5], v[194:195]
	v_mov_b64_e32 v[6:7], v[196:197]
	s_nop 0
	v_mov_b64_e32 v[20:21], v[232:233]
	v_add_f32_e32 v134, v108, v109
	v_mov_b64_e32 v[22:23], v[238:239]
	v_add_f32_e32 v136, v110, v111
	v_lshlrev_b32_e32 v104, 16, v20
	v_and_b32_e32 v105, 0xffff0000, v20
	v_lshlrev_b32_e32 v20, 16, v21
	v_and_b32_e32 v21, 0xffff0000, v21
	v_lshlrev_b32_e32 v106, 16, v22
	v_and_b32_e32 v107, 0xffff0000, v22
	v_lshlrev_b32_e32 v22, 16, v23
	v_and_b32_e32 v23, 0xffff0000, v23
	v_pk_add_f32 v[20:21], v[20:21], v[22:23]
	v_pk_add_f32 v[22:23], v[104:105], v[106:107]
	v_pk_mul_f32 v[6:7], v[6:7], v[20:21]
	v_pk_mul_f32 v[4:5], v[4:5], v[22:23]
	v_pk_fma_f32 v[106:107], v[2:3], s[42:43], v[6:7] op_sel_hi:[1,0,1]
	v_pk_fma_f32 v[104:105], v[0:1], s[42:43], v[4:5] op_sel_hi:[1,0,1]
	v_mov_b32_e32 v135, v106
	v_mov_b32_e32 v131, v104
	v_mov_b32_e32 v133, v105
	v_mov_b32_e32 v137, v107
	v_pk_add_f32 v[0:1], v[130:131], v[132:133]
	v_pk_add_f32 v[2:3], v[134:135], v[136:137]
	ds_bpermute_b32 v22, v67, v126
	v_pk_add_f32 v[0:1], v[0:1], v[2:3]
	s_waitcnt lgkmcnt(0)
	v_add_f32_e32 v22, v126, v22
	v_add_f32_e32 v65, v0, v1
	ds_bpermute_b32 v0, v67, v122
	ds_bpermute_b32 v23, v69, v22
	s_waitcnt lgkmcnt(1)
	v_add_f32_e32 v0, v122, v0
	ds_bpermute_b32 v1, v69, v0
	s_waitcnt lgkmcnt(1)
	v_add_f32_e32 v22, v22, v23
	ds_bpermute_b32 v23, v71, v22
	s_waitcnt lgkmcnt(1)
	v_add_f32_e32 v0, v0, v1
	ds_bpermute_b32 v1, v71, v0
	s_waitcnt lgkmcnt(1)
	v_add_f32_e32 v22, v22, v23
	ds_bpermute_b32 v23, v73, v22
	s_waitcnt lgkmcnt(1)
	v_add_f32_e32 v0, v0, v1
	ds_bpermute_b32 v1, v73, v0
	s_waitcnt lgkmcnt(1)
	v_add_f32_e32 v22, v22, v23
	ds_bpermute_b32 v23, v123, v22
	s_waitcnt lgkmcnt(1)
	v_add_f32_e32 v0, v0, v1
	ds_bpermute_b32 v1, v123, v0
	s_waitcnt lgkmcnt(1)
	v_add_f32_e32 v22, v22, v23
	ds_bpermute_b32 v23, v124, v22
	s_waitcnt lgkmcnt(1)
	v_add_f32_e32 v0, v0, v1
	ds_bpermute_b32 v1, v124, v0
	s_waitcnt lgkmcnt(1)
	v_add_f32_e32 v122, v22, v23
	v_fmamk_f32 v29, v122, 0xba800000, v29
	v_fmac_f32_e32 v28, 0xba800000, v122
	v_fmamk_f32 v31, v122, 0xba800000, v31
	s_waitcnt lgkmcnt(0)
	v_add_f32_e32 v20, v0, v1
	v_fmamk_f32 v9, v20, 0xba800000, v9
	v_fmac_f32_e32 v8, 0xba800000, v20
	v_fmamk_f32 v11, v20, 0xba800000, v11
	v_fmac_f32_e32 v10, 0xba800000, v20
	v_pk_mul_f32 v[0:1], v[10:11], v[10:11]
	v_pk_mul_f32 v[2:3], v[8:9], v[8:9]
	v_fmamk_f32 v13, v20, 0xba800000, v13
	v_pk_mov_b32 v[4:5], v[2:3], v[0:1] op_sel:[1,0]
	v_mov_b32_e32 v3, v1
	v_pk_add_f32 v[0:1], v[4:5], v[2:3]
	v_fmac_f32_e32 v12, 0xba800000, v20
	v_fmamk_f32 v15, v20, 0xba800000, v15
	v_fmac_f32_e32 v14, 0xba800000, v20
	v_pk_add_f32 v[0:1], v[0:1], v[0:1] op_sel_hi:[0,1]
	v_pk_mul_f32 v[2:3], v[14:15], v[14:15]
	v_pk_mul_f32 v[4:5], v[12:13], v[12:13]
	v_fmac_f32_e32 v16, 0xba800000, v20
	v_pk_mov_b32 v[6:7], v[4:5], v[2:3] op_sel:[1,0]
	v_mov_b32_e32 v5, v3
	v_fmamk_f32 v17, v20, 0xba800000, v17
	v_fmac_f32_e32 v18, 0xba800000, v20
	v_mul_f32_e32 v0, v16, v16
	v_pk_add_f32 v[2:3], v[6:7], v[4:5]
	v_fmamk_f32 v19, v20, 0xba800000, v19
	v_pk_fma_f32 v[4:5], v[16:17], v[16:17], v[0:1] op_sel_hi:[1,1,0]
	v_mul_f32_e32 v0, v18, v18
	v_pk_add_f32 v[2:3], v[2:3], v[2:3] op_sel_hi:[0,1]
	v_pk_fma_f32 v[6:7], v[18:19], v[18:19], v[0:1] op_sel_hi:[1,1,0]
	v_fmamk_f32 v27, v20, 0xba800000, v27
	v_fmac_f32_e32 v26, 0xba800000, v20
	v_fmamk_f32 v25, v20, 0xba800000, v25
	v_fmac_f32_e32 v24, 0xba800000, v20
	v_mul_f32_e32 v4, v24, v24
	v_mul_f32_e32 v6, v25, v25
	v_mul_f32_e32 v0, v26, v26
	v_mul_f32_e32 v2, v27, v27
	v_pk_add_f32 v[4:5], v[4:5], v[6:7]
	v_pk_add_f32 v[0:1], v[0:1], v[2:3]
	v_fmac_f32_e32 v30, 0xba800000, v122
	v_pk_add_f32 v[20:21], v[4:5], v[0:1]
	v_mov_b64_e32 v[0:1], v[154:155]
	v_mov_b64_e32 v[2:3], v[156:157]
	v_mov_b64_e32 v[4:5], v[158:159]
	v_mov_b64_e32 v[6:7], v[160:161]
	v_pk_mul_f32 v[22:23], v[30:31], v[30:31]
	v_pk_mul_f32 v[120:121], v[28:29], v[28:29]
	v_fmamk_f32 v39, v122, 0xba800000, v39
	v_pk_mov_b32 v[126:127], v[120:121], v[22:23] op_sel:[1,0]
	v_mov_b32_e32 v121, v23
	v_pk_add_f32 v[22:23], v[126:127], v[120:121]
	v_fmac_f32_e32 v38, 0xba800000, v122
	v_fmamk_f32 v61, v122, 0xba800000, v61
	v_fmac_f32_e32 v60, 0xba800000, v122
	v_pk_add_f32 v[22:23], v[22:23], v[22:23] op_sel_hi:[0,1]
	v_pk_mul_f32 v[120:121], v[60:61], v[60:61]
	v_pk_mul_f32 v[126:127], v[38:39], v[38:39]
	v_fmac_f32_e32 v34, 0xba800000, v122
	v_pk_mov_b32 v[128:129], v[126:127], v[120:121] op_sel:[1,0]
	v_mov_b32_e32 v127, v121
	v_fmamk_f32 v35, v122, 0xba800000, v35
	v_fmac_f32_e32 v36, 0xba800000, v122
	v_mul_f32_e32 v22, v34, v34
	v_pk_add_f32 v[120:121], v[128:129], v[126:127]
	v_fmamk_f32 v37, v122, 0xba800000, v37
	v_pk_fma_f32 v[126:127], v[34:35], v[34:35], v[22:23] op_sel_hi:[1,1,0]
	v_mul_f32_e32 v22, v36, v36
	v_pk_add_f32 v[120:121], v[120:121], v[120:121] op_sel_hi:[0,1]
	v_pk_fma_f32 v[128:129], v[36:37], v[36:37], v[22:23] op_sel_hi:[1,1,0]
	v_fmamk_f32 v119, v122, 0xba800000, v119
	v_fmac_f32_e32 v118, 0xba800000, v122
	v_fmamk_f32 v63, v122, 0xba800000, v63
	v_fmac_f32_e32 v62, 0xba800000, v122
	v_mul_f32_e32 v126, v62, v62
	v_mul_f32_e32 v128, v63, v63
	v_mul_f32_e32 v22, v118, v118
	v_mul_f32_e32 v120, v119, v119
	v_pk_add_f32 v[126:127], v[126:127], v[128:129]
	v_pk_add_f32 v[22:23], v[22:23], v[120:121]
	v_mov_b32_e32 v121, v20
	v_pk_add_f32 v[22:23], v[126:127], v[22:23]
	s_nop 0
	v_mov_b32_e32 v120, v22
	v_mov_b32_e32 v20, v23
	v_pk_add_f32 v[20:21], v[120:121], v[20:21]
	ds_bpermute_b32 v23, v67, v21
	ds_bpermute_b32 v22, v67, v20
	v_mov_b64_e32 v[120:121], s[2:3]
	s_mov_b32 s2, 0x3a800000
	s_waitcnt lgkmcnt(0)
	v_pk_add_f32 v[20:21], v[20:21], v[22:23]
	ds_bpermute_b32 v23, v69, v21
	ds_bpermute_b32 v22, v69, v20
	s_waitcnt lgkmcnt(0)
	v_pk_add_f32 v[20:21], v[20:21], v[22:23]
	ds_bpermute_b32 v23, v71, v21
	ds_bpermute_b32 v22, v71, v20
	s_waitcnt lgkmcnt(0)
	v_pk_add_f32 v[20:21], v[20:21], v[22:23]
	ds_bpermute_b32 v23, v73, v21
	ds_bpermute_b32 v22, v73, v20
	s_waitcnt lgkmcnt(0)
	v_pk_add_f32 v[20:21], v[20:21], v[22:23]
	ds_bpermute_b32 v23, v123, v21
	ds_bpermute_b32 v22, v123, v20
	s_waitcnt lgkmcnt(0)
	v_pk_add_f32 v[20:21], v[20:21], v[22:23]
	ds_bpermute_b32 v23, v124, v21
	ds_bpermute_b32 v22, v124, v20
	s_waitcnt lgkmcnt(0)
	v_pk_add_f32 v[20:21], v[20:21], v[22:23]
	s_nop 0
	v_pk_fma_f32 v[126:127], v[20:21], s[2:3], v[120:121] op_sel_hi:[1,0,0]
	s_nop 0
	v_mul_f32_e32 v20, 0x4b800000, v127
	v_cmp_gt_f32_e64 s[8:9], s68, v127
	v_cmp_gt_f32_e32 vcc, s68, v126
	s_nop 0
	v_cndmask_b32_e64 v20, v127, v20, s[8:9]
	v_rsq_f32_e32 v20, v20
	s_nop 0
	v_mul_f32_e32 v21, 0x45800000, v20
	v_cndmask_b32_e64 v122, v20, v21, s[8:9]
	v_pk_mul_f32 v[8:9], v[8:9], v[122:123] op_sel_hi:[1,0]
	v_pk_mul_f32 v[10:11], v[10:11], v[122:123] op_sel_hi:[1,0]
	v_pk_fma_f32 v[20:21], v[0:1], v[8:9], v[4:5]
	v_pk_fma_f32 v[22:23], v[2:3], v[10:11], v[6:7]
	flat_store_dwordx4 v[86:87], v[20:23]
	v_mov_b64_e32 v[0:1], v[162:163]
	v_mov_b64_e32 v[2:3], v[164:165]
	v_mov_b64_e32 v[4:5], v[166:167]
	v_mov_b64_e32 v[6:7], v[168:169]
	v_pk_mul_f32 v[8:9], v[14:15], v[122:123] op_sel_hi:[1,0]
	v_pk_mul_f32 v[10:11], v[12:13], v[122:123] op_sel_hi:[1,0]
	v_pk_fma_f32 v[14:15], v[2:3], v[8:9], v[6:7]
	v_pk_fma_f32 v[12:13], v[0:1], v[10:11], v[4:5]
	flat_store_dwordx4 v[86:87], v[12:15] offset:1024
	v_mov_b64_e32 v[0:1], v[170:171]
	v_mov_b64_e32 v[2:3], v[172:173]
	v_mov_b64_e32 v[4:5], v[174:175]
	v_mov_b64_e32 v[6:7], v[176:177]
	v_pk_mul_f32 v[8:9], v[18:19], v[122:123] op_sel_hi:[1,0]
	v_pk_mul_f32 v[10:11], v[16:17], v[122:123] op_sel_hi:[1,0]
	v_pk_mul_f32 v[18:19], v[24:25], v[122:123] op_sel_hi:[1,0]
	v_pk_mul_f32 v[16:17], v[26:27], v[122:123] op_sel_hi:[1,0]
	v_pk_fma_f32 v[4:5], v[0:1], v[10:11], v[4:5]
	v_pk_fma_f32 v[6:7], v[2:3], v[8:9], v[6:7]
	flat_store_dwordx4 v[86:87], v[4:7] offset:2048
	v_mov_b64_e32 v[0:1], v[178:179]
	v_mov_b64_e32 v[2:3], v[180:181]
	v_mov_b64_e32 v[8:9], v[182:183]
	v_mov_b64_e32 v[10:11], v[184:185]
	v_pk_fma_f32 v[0:1], v[0:1], v[18:19], v[8:9]
	v_mul_f32_e32 v8, 0x4b800000, v126
	v_cndmask_b32_e32 v8, v126, v8, vcc
	v_rsq_f32_e32 v8, v8
	v_pk_fma_f32 v[2:3], v[2:3], v[16:17], v[10:11]
	flat_store_dwordx4 v[86:87], v[0:3] offset:3072
	v_mul_f32_e32 v9, 0x45800000, v8
	v_cndmask_b32_e32 v122, v8, v9, vcc
	v_mov_b64_e32 v[8:9], v[154:155]
	v_mov_b64_e32 v[10:11], v[156:157]
	v_mov_b64_e32 v[16:17], v[158:159]
	v_mov_b64_e32 v[18:19], v[160:161]
	v_pk_mul_f32 v[24:25], v[30:31], v[122:123] op_sel_hi:[1,0]
	v_pk_mul_f32 v[26:27], v[28:29], v[122:123] op_sel_hi:[1,0]
	v_pk_mul_f32 v[30:31], v[60:61], v[122:123] op_sel_hi:[1,0]
	v_pk_mul_f32 v[28:29], v[38:39], v[122:123] op_sel_hi:[1,0]
	v_pk_mul_f32 v[36:37], v[36:37], v[122:123] op_sel_hi:[1,0]
	v_pk_mul_f32 v[34:35], v[34:35], v[122:123] op_sel_hi:[1,0]
	v_pk_mul_f32 v[38:39], v[118:119], v[122:123] op_sel_hi:[1,0]
	v_pk_mul_f32 v[60:61], v[62:63], v[122:123] op_sel_hi:[1,0]
	ds_bpermute_b32 v62, v67, v65
	s_waitcnt lgkmcnt(0)
	v_add_f32_e32 v62, v65, v62
	ds_bpermute_b32 v63, v69, v62
	s_waitcnt lgkmcnt(0)
	v_add_f32_e32 v62, v62, v63
	ds_bpermute_b32 v63, v71, v62
	s_waitcnt lgkmcnt(0)
	v_add_f32_e32 v62, v62, v63
	ds_bpermute_b32 v63, v73, v62
	s_waitcnt lgkmcnt(0)
	v_add_f32_e32 v62, v62, v63
	ds_bpermute_b32 v63, v123, v62
	s_waitcnt lgkmcnt(0)
	v_add_f32_e32 v62, v62, v63
	ds_bpermute_b32 v63, v124, v62
	s_waitcnt lgkmcnt(0)
	v_add_f32_e32 v65, v62, v63
	v_fmamk_f32 v45, v65, 0xba800000, v45
	v_fmac_f32_e32 v44, 0xba800000, v65
	v_fmamk_f32 v115, v65, 0xba800000, v115
	v_fmac_f32_e32 v114, 0xba800000, v65
	v_pk_mul_f32 v[62:63], v[114:115], v[114:115]
	v_pk_mul_f32 v[118:119], v[44:45], v[44:45]
	v_fmamk_f32 v43, v65, 0xba800000, v43
	v_pk_mov_b32 v[126:127], v[118:119], v[62:63] op_sel:[1,0]
	v_mov_b32_e32 v119, v63
	v_pk_add_f32 v[62:63], v[126:127], v[118:119]
	v_fmac_f32_e32 v42, 0xba800000, v65
	v_fmamk_f32 v113, v65, 0xba800000, v113
	v_fmac_f32_e32 v112, 0xba800000, v65
	v_pk_add_f32 v[62:63], v[62:63], v[62:63] op_sel_hi:[0,1]
	v_pk_mul_f32 v[118:119], v[112:113], v[112:113]
	v_pk_mul_f32 v[126:127], v[42:43], v[42:43]
	v_fmac_f32_e32 v108, 0xba800000, v65
	v_pk_mov_b32 v[128:129], v[126:127], v[118:119] op_sel:[1,0]
	v_mov_b32_e32 v127, v119
	v_fmamk_f32 v109, v65, 0xba800000, v109
	v_fmac_f32_e32 v110, 0xba800000, v65
	v_mul_f32_e32 v62, v108, v108
	v_pk_add_f32 v[118:119], v[128:129], v[126:127]
	v_fmamk_f32 v111, v65, 0xba800000, v111
	v_pk_fma_f32 v[126:127], v[108:109], v[108:109], v[62:63] op_sel_hi:[1,1,0]
	v_mul_f32_e32 v62, v110, v110
	v_pk_add_f32 v[118:119], v[118:119], v[118:119] op_sel_hi:[0,1]
	v_pk_fma_f32 v[128:129], v[110:111], v[110:111], v[62:63] op_sel_hi:[1,1,0]
	v_fmamk_f32 v107, v65, 0xba800000, v107
	v_fmac_f32_e32 v106, 0xba800000, v65
	v_fmamk_f32 v105, v65, 0xba800000, v105
	v_fmac_f32_e32 v104, 0xba800000, v65
	v_mul_f32_e32 v126, v104, v104
	v_mul_f32_e32 v128, v105, v105
	v_mul_f32_e32 v62, v106, v106
	v_pk_fma_f32 v[8:9], v[8:9], v[26:27], v[16:17]
	v_pk_fma_f32 v[10:11], v[10:11], v[24:25], v[18:19]
	flat_store_dwordx4 v[32:33], v[8:11]
	v_mov_b64_e32 v[16:17], v[162:163]
	v_mov_b64_e32 v[18:19], v[164:165]
	v_mov_b64_e32 v[24:25], v[166:167]
	v_mov_b64_e32 v[26:27], v[168:169]
	v_mul_f32_e32 v118, v107, v107
	v_pk_add_f32 v[126:127], v[126:127], v[128:129]
	v_pk_add_f32 v[62:63], v[62:63], v[118:119]
	v_pk_fma_f32 v[28:29], v[16:17], v[28:29], v[24:25]
	v_pk_fma_f32 v[30:31], v[18:19], v[30:31], v[26:27]
	flat_store_dwordx4 v[32:33], v[28:31] offset:1024
	v_mov_b64_e32 v[16:17], v[170:171]
	v_mov_b64_e32 v[18:19], v[172:173]
	v_mov_b64_e32 v[24:25], v[174:175]
	v_mov_b64_e32 v[26:27], v[176:177]
	v_pk_add_f32 v[62:63], v[126:127], v[62:63]
	v_pk_fma_f32 v[24:25], v[16:17], v[34:35], v[24:25]
	v_pk_fma_f32 v[26:27], v[18:19], v[36:37], v[26:27]
	flat_store_dwordx4 v[32:33], v[24:27] offset:2048
	v_mov_b64_e32 v[16:17], v[178:179]
	v_mov_b64_e32 v[18:19], v[180:181]
	v_mov_b64_e32 v[34:35], v[182:183]
	v_mov_b64_e32 v[36:37], v[184:185]
	v_mov_b32_e32 v118, v62
	v_pk_fma_f32 v[16:17], v[16:17], v[60:61], v[34:35]
	v_pk_fma_f32 v[18:19], v[18:19], v[38:39], v[36:37]
	flat_store_dwordx4 v[32:33], v[16:19] offset:3072
	ds_bpermute_b32 v32, v67, v125
	s_waitcnt lgkmcnt(0)
	v_add_f32_e32 v32, v125, v32
	ds_bpermute_b32 v33, v69, v32
	s_waitcnt lgkmcnt(0)
	v_add_f32_e32 v32, v32, v33
	ds_bpermute_b32 v33, v71, v32
	s_waitcnt lgkmcnt(0)
	v_add_f32_e32 v32, v32, v33
	ds_bpermute_b32 v33, v73, v32
	s_waitcnt lgkmcnt(0)
	v_add_f32_e32 v32, v32, v33
	ds_bpermute_b32 v33, v123, v32
	s_waitcnt lgkmcnt(0)
	v_add_f32_e32 v32, v32, v33
	ds_bpermute_b32 v33, v124, v32
	s_waitcnt lgkmcnt(0)
	v_add_f32_e32 v60, v32, v33
	v_fmamk_f32 v51, v60, 0xba800000, v51
	v_fmac_f32_e32 v50, 0xba800000, v60
	v_fmamk_f32 v53, v60, 0xba800000, v53
	v_fmac_f32_e32 v52, 0xba800000, v60
	v_pk_mul_f32 v[32:33], v[52:53], v[52:53]
	v_pk_mul_f32 v[34:35], v[50:51], v[50:51]
	v_fmamk_f32 v57, v60, 0xba800000, v57
	v_pk_mov_b32 v[36:37], v[34:35], v[32:33] op_sel:[1,0]
	v_mov_b32_e32 v35, v33
	v_pk_add_f32 v[32:33], v[36:37], v[34:35]
	v_fmac_f32_e32 v56, 0xba800000, v60
	v_fmamk_f32 v59, v60, 0xba800000, v59
	v_fmac_f32_e32 v58, 0xba800000, v60
	v_pk_add_f32 v[32:33], v[32:33], v[32:33] op_sel_hi:[0,1]
	v_pk_mul_f32 v[34:35], v[58:59], v[58:59]
	v_pk_mul_f32 v[36:37], v[56:57], v[56:57]
	v_fmac_f32_e32 v54, 0xba800000, v60
	v_pk_mov_b32 v[38:39], v[36:37], v[34:35] op_sel:[1,0]
	v_mov_b32_e32 v37, v35
	v_fmamk_f32 v55, v60, 0xba800000, v55
	v_fmac_f32_e32 v116, 0xba800000, v60
	v_mul_f32_e32 v32, v54, v54
	v_pk_add_f32 v[34:35], v[38:39], v[36:37]
	v_fmamk_f32 v117, v60, 0xba800000, v117
	v_pk_fma_f32 v[36:37], v[54:55], v[54:55], v[32:33] op_sel_hi:[1,1,0]
	v_mul_f32_e32 v32, v116, v116
	v_pk_add_f32 v[34:35], v[34:35], v[34:35] op_sel_hi:[0,1]
	v_pk_fma_f32 v[38:39], v[116:117], v[116:117], v[32:33] op_sel_hi:[1,1,0]
	v_fmamk_f32 v49, v60, 0xba800000, v49
	v_fmac_f32_e32 v48, 0xba800000, v60
	v_fmamk_f32 v47, v60, 0xba800000, v47
	v_fmac_f32_e32 v46, 0xba800000, v60
	v_mul_f32_e32 v36, v46, v46
	v_mul_f32_e32 v38, v47, v47
	v_mul_f32_e32 v32, v48, v48
	v_mul_f32_e32 v34, v49, v49
	v_pk_add_f32 v[36:37], v[36:37], v[38:39]
	v_pk_add_f32 v[32:33], v[32:33], v[34:35]
	s_nop 0
	v_pk_add_f32 v[60:61], v[36:37], v[32:33]
	v_mov_b64_e32 v[32:33], v[154:155]
	v_mov_b64_e32 v[34:35], v[156:157]
	v_mov_b64_e32 v[36:37], v[158:159]
	v_mov_b64_e32 v[38:39], v[160:161]
	v_mov_b32_e32 v119, v60
	v_mov_b32_e32 v60, v63
	v_pk_add_f32 v[60:61], v[118:119], v[60:61]
	ds_bpermute_b32 v63, v67, v61
	ds_bpermute_b32 v62, v67, v60
	s_waitcnt lgkmcnt(0)
	v_pk_add_f32 v[60:61], v[60:61], v[62:63]
	ds_bpermute_b32 v63, v69, v61
	ds_bpermute_b32 v62, v69, v60
	s_waitcnt lgkmcnt(0)
	v_pk_add_f32 v[60:61], v[60:61], v[62:63]
	ds_bpermute_b32 v63, v71, v61
	ds_bpermute_b32 v62, v71, v60
	s_waitcnt lgkmcnt(0)
	v_pk_add_f32 v[60:61], v[60:61], v[62:63]
	ds_bpermute_b32 v63, v73, v61
	ds_bpermute_b32 v62, v73, v60
	s_waitcnt lgkmcnt(0)
	v_pk_add_f32 v[60:61], v[60:61], v[62:63]
	ds_bpermute_b32 v63, v123, v61
	ds_bpermute_b32 v62, v123, v60
	s_waitcnt lgkmcnt(0)
	v_pk_add_f32 v[60:61], v[60:61], v[62:63]
	ds_bpermute_b32 v63, v124, v61
	ds_bpermute_b32 v62, v124, v60
	s_waitcnt lgkmcnt(0)
	v_pk_add_f32 v[60:61], v[60:61], v[62:63]
	s_nop 0
	v_pk_fma_f32 v[118:119], v[60:61], s[2:3], v[120:121] op_sel_hi:[1,0,0]
	s_nop 0
	v_mul_f32_e32 v60, 0x4b800000, v119
	v_cmp_gt_f32_e64 s[8:9], s68, v119
	v_cmp_gt_f32_e32 vcc, s68, v118
	s_nop 0
	v_cndmask_b32_e64 v60, v119, v60, s[8:9]
	v_rsq_f32_e32 v60, v60
	s_nop 0
	v_mul_f32_e32 v61, 0x45800000, v60
	v_cndmask_b32_e64 v120, v60, v61, s[8:9]
	v_pk_mul_f32 v[52:53], v[52:53], v[120:121] op_sel_hi:[1,0]
	v_pk_mul_f32 v[50:51], v[50:51], v[120:121] op_sel_hi:[1,0]
	v_pk_mul_f32 v[46:47], v[46:47], v[120:121] op_sel_hi:[1,0]
	v_pk_fma_f32 v[60:61], v[32:33], v[50:51], v[36:37]
	v_pk_fma_f32 v[62:63], v[34:35], v[52:53], v[38:39]
	flat_store_dwordx4 v[40:41], v[60:63]
	v_mov_b64_e32 v[32:33], v[162:163]
	v_mov_b64_e32 v[34:35], v[164:165]
	v_mov_b64_e32 v[36:37], v[166:167]
	v_mov_b64_e32 v[38:39], v[168:169]
	v_pk_mul_f32 v[50:51], v[58:59], v[120:121] op_sel_hi:[1,0]
	v_pk_mul_f32 v[52:53], v[56:57], v[120:121] op_sel_hi:[1,0]
	v_pk_fma_f32 v[58:59], v[34:35], v[50:51], v[38:39]
	v_pk_fma_f32 v[56:57], v[32:33], v[52:53], v[36:37]
	flat_store_dwordx4 v[40:41], v[56:59] offset:1024
	v_mov_b64_e32 v[32:33], v[170:171]
	v_mov_b64_e32 v[34:35], v[172:173]
	v_mov_b64_e32 v[36:37], v[174:175]
	v_mov_b64_e32 v[38:39], v[176:177]
	v_pk_mul_f32 v[50:51], v[116:117], v[120:121] op_sel_hi:[1,0]
	v_pk_mul_f32 v[52:53], v[54:55], v[120:121] op_sel_hi:[1,0]
	v_pk_fma_f32 v[54:55], v[34:35], v[50:51], v[38:39]
	v_pk_fma_f32 v[52:53], v[32:33], v[52:53], v[36:37]
	flat_store_dwordx4 v[40:41], v[52:55] offset:2048
	v_mov_b64_e32 v[32:33], v[178:179]
	v_mov_b64_e32 v[34:35], v[180:181]
	v_mov_b64_e32 v[36:37], v[182:183]
	v_mov_b64_e32 v[38:39], v[184:185]
	v_pk_mul_f32 v[50:51], v[48:49], v[120:121] op_sel_hi:[1,0]
	v_pk_fma_f32 v[48:49], v[32:33], v[46:47], v[36:37]
	v_mul_f32_e32 v32, 0x4b800000, v118
	v_cndmask_b32_e32 v32, v118, v32, vcc
	v_rsq_f32_e32 v32, v32
	v_pk_fma_f32 v[50:51], v[34:35], v[50:51], v[38:39]
	flat_store_dwordx4 v[40:41], v[48:51] offset:3072
	v_mul_f32_e32 v33, 0x45800000, v32
	v_cndmask_b32_e32 v116, v32, v33, vcc
	v_mov_b64_e32 v[32:33], v[154:155]
	v_mov_b64_e32 v[34:35], v[156:157]
	v_mov_b64_e32 v[36:37], v[158:159]
	v_mov_b64_e32 v[38:39], v[160:161]
	v_pk_mul_f32 v[40:41], v[114:115], v[116:117] op_sel_hi:[1,0]
	v_pk_mul_f32 v[44:45], v[44:45], v[116:117] op_sel_hi:[1,0]
	v_pk_mul_f32 v[112:113], v[112:113], v[116:117] op_sel_hi:[1,0]
	v_pk_mul_f32 v[110:111], v[110:111], v[116:117] op_sel_hi:[1,0]
	v_pk_mul_f32 v[108:109], v[108:109], v[116:117] op_sel_hi:[1,0]
	s_andn2_b64 vcc, exec, s[4:5]
	v_pk_fma_f32 v[44:45], v[32:33], v[44:45], v[36:37]
	v_pk_fma_f32 v[46:47], v[34:35], v[40:41], v[38:39]
	flat_store_dwordx4 v[102:103], v[44:47]
	v_mov_b64_e32 v[32:33], v[162:163]
	v_mov_b64_e32 v[34:35], v[164:165]
	v_mov_b64_e32 v[36:37], v[166:167]
	v_mov_b64_e32 v[38:39], v[168:169]
	v_pk_mul_f32 v[40:41], v[42:43], v[116:117] op_sel_hi:[1,0]
	v_pk_fma_f32 v[42:43], v[34:35], v[112:113], v[38:39]
	v_pk_fma_f32 v[40:41], v[32:33], v[40:41], v[36:37]
	flat_store_dwordx4 v[102:103], v[40:43] offset:1024
	v_mov_b64_e32 v[32:33], v[170:171]
	v_mov_b64_e32 v[34:35], v[172:173]
	v_mov_b64_e32 v[36:37], v[174:175]
	v_mov_b64_e32 v[38:39], v[176:177]
	v_pk_fma_f32 v[36:37], v[32:33], v[108:109], v[36:37]
	v_pk_fma_f32 v[38:39], v[34:35], v[110:111], v[38:39]
	flat_store_dwordx4 v[102:103], v[36:39] offset:2048
	v_pk_mul_f32 v[108:109], v[106:107], v[116:117] op_sel_hi:[1,0]
	v_pk_mul_f32 v[110:111], v[104:105], v[116:117] op_sel_hi:[1,0]
	v_mov_b64_e32 v[32:33], v[178:179]
	v_mov_b64_e32 v[34:35], v[180:181]
	v_mov_b64_e32 v[104:105], v[182:183]
	v_mov_b64_e32 v[106:107], v[184:185]
	v_pk_fma_f32 v[32:33], v[32:33], v[110:111], v[104:105]
	v_pk_fma_f32 v[34:35], v[34:35], v[108:109], v[106:107]
	flat_store_dwordx4 v[102:103], v[32:35] offset:3072
	s_cbranch_vccnz .LBB0_50
	v_mad_u64_u32 v[104:105], s[4:5], v88, s7, 0
	v_mad_u64_u32 v[102:103], s[4:5], v92, s7, 0
	v_mad_i32_i24 v105, v89, s7, v105
	v_mad_i32_i24 v103, v93, s7, v103
	v_mad_u64_u32 v[92:93], s[4:5], v98, s7, 0
	v_mad_u64_u32 v[88:89], s[4:5], v100, s7, 0
	v_mad_i32_i24 v93, v99, s7, v93
	v_lshl_add_u64 v[98:99], s[60:61], 0, v[104:105]
	s_mov_b64 s[4:5], 0x6000
	s_mov_b64 s[8:9], 0x7000
	v_mad_i32_i24 v89, v101, s7, v89
	v_lshl_add_u64 v[100:101], v[98:99], 0, s[4:5]
	v_lshl_add_u64 v[98:99], v[98:99], 0, s[8:9]
	v_lshlrev_b32_e32 v152, 2, v66
	v_lshl_add_u64 v[104:105], v[100:101], 0, v[152:153]
	v_lshl_add_u64 v[108:109], v[98:99], 0, v[152:153]
	global_load_dwordx4 v[186:189], v[104:105], off offset:1024
	global_load_dwordx4 v[190:193], v[104:105], off offset:2048
	global_load_dwordx4 v[194:197], v[104:105], off offset:3072
	flat_load_dwordx4 v[104:107], v[104:105]
	s_nop 0
	global_load_dwordx4 v[198:201], v[108:109], off offset:1024
	global_load_dwordx4 v[202:205], v[108:109], off offset:2048
	global_load_dwordx4 v[224:227], v[108:109], off offset:3072
	flat_load_dwordx4 v[108:111], v[108:109]
	s_waitcnt vmcnt(0) lgkmcnt(0)
	v_pk_add_f32 v[110:111], v[110:111], 1.0 op_sel_hi:[1,0]
	v_pk_add_f32 v[108:109], v[108:109], 1.0 op_sel_hi:[1,0]
	v_pk_fma_f32 v[22:23], v[22:23], v[110:111], v[106:107]
	v_pk_fma_f32 v[20:21], v[20:21], v[108:109], v[104:105]
	s_nop 0
	v_cvt_pk_bf16_f32 v20, v20, v21
	v_cvt_pk_bf16_f32 v21, v22, v23
	flat_store_dwordx2 v[84:85], v[20:21]
	v_lshlrev_b32_e32 v20, 2, v68
	v_mov_b32_e32 v21, v153
	v_lshl_add_u64 v[22:23], v[100:101], 0, v[20:21]
	v_mov_b64_e32 v[104:105], v[186:187]
	v_mov_b64_e32 v[106:107], v[188:189]
	v_lshl_add_u64 v[22:23], v[98:99], 0, v[20:21]
	v_mov_b64_e32 v[108:109], v[198:199]
	v_mov_b64_e32 v[110:111], v[200:201]
	v_pk_add_f32 v[22:23], v[110:111], 1.0 op_sel_hi:[1,0]
	v_pk_add_f32 v[108:109], v[108:109], 1.0 op_sel_hi:[1,0]
	v_pk_fma_f32 v[14:15], v[14:15], v[22:23], v[106:107]
	v_pk_fma_f32 v[12:13], v[12:13], v[108:109], v[104:105]
	s_nop 0
	v_cvt_pk_bf16_f32 v12, v12, v13
	v_cvt_pk_bf16_f32 v13, v14, v15
	flat_store_dwordx2 v[84:85], v[12:13] offset:512
	v_lshlrev_b32_e32 v12, 2, v70
	v_mov_b32_e32 v13, v153
	v_lshl_add_u64 v[14:15], v[100:101], 0, v[12:13]
	v_mov_b64_e32 v[104:105], v[190:191]
	v_mov_b64_e32 v[106:107], v[192:193]
	v_lshl_add_u64 v[14:15], v[98:99], 0, v[12:13]
	v_mov_b64_e32 v[108:109], v[202:203]
	v_mov_b64_e32 v[110:111], v[204:205]
	v_pk_add_f32 v[14:15], v[110:111], 1.0 op_sel_hi:[1,0]
	v_pk_add_f32 v[22:23], v[108:109], 1.0 op_sel_hi:[1,0]
	v_pk_fma_f32 v[6:7], v[6:7], v[14:15], v[106:107]
	v_pk_fma_f32 v[4:5], v[4:5], v[22:23], v[104:105]
	s_nop 0
	v_cvt_pk_bf16_f32 v4, v4, v5
	v_cvt_pk_bf16_f32 v5, v6, v7
	flat_store_dwordx2 v[84:85], v[4:5] offset:1024
	v_lshlrev_b32_e32 v4, 2, v72
	v_mov_b32_e32 v5, v153
	v_lshl_add_u64 v[6:7], v[100:101], 0, v[4:5]
	v_mov_b64_e32 v[104:105], v[194:195]
	v_mov_b64_e32 v[106:107], v[196:197]
	v_lshl_add_u64 v[6:7], v[98:99], 0, v[4:5]
	v_mov_b64_e32 v[98:99], v[224:225]
	v_mov_b64_e32 v[100:101], v[226:227]
	v_pk_add_f32 v[6:7], v[100:101], 1.0 op_sel_hi:[1,0]
	v_pk_add_f32 v[14:15], v[98:99], 1.0 op_sel_hi:[1,0]
	v_pk_fma_f32 v[2:3], v[2:3], v[6:7], v[106:107]
	v_pk_fma_f32 v[0:1], v[0:1], v[14:15], v[104:105]
	s_nop 0
	v_cvt_pk_bf16_f32 v0, v0, v1
	v_cvt_pk_bf16_f32 v1, v2, v3
	flat_store_dwordx2 v[84:85], v[0:1] offset:1536
	v_lshl_add_u64 v[0:1], s[60:61], 0, v[102:103]
	v_lshl_add_u64 v[2:3], v[0:1], 0, s[4:5]
	v_lshl_add_u64 v[0:1], v[0:1], 0, s[8:9]
	v_lshl_add_u64 v[6:7], v[2:3], 0, v[152:153]
	global_load_dwordx4 v[186:189], v[6:7], off offset:1024
	global_load_dwordx4 v[190:193], v[6:7], off offset:2048
	global_load_dwordx4 v[194:197], v[6:7], off offset:3072
	flat_load_dwordx4 v[98:101], v[6:7]
	v_lshl_add_u64 v[6:7], v[0:1], 0, v[152:153]
	global_load_dwordx4 v[198:201], v[6:7], off offset:1024
	global_load_dwordx4 v[202:205], v[6:7], off offset:2048
	global_load_dwordx4 v[224:227], v[6:7], off offset:3072
	flat_load_dwordx4 v[102:105], v[6:7]
	s_waitcnt vmcnt(0) lgkmcnt(0)
	v_pk_add_f32 v[6:7], v[104:105], 1.0 op_sel_hi:[1,0]
	v_pk_add_f32 v[14:15], v[102:103], 1.0 op_sel_hi:[1,0]
	v_pk_fma_f32 v[6:7], v[10:11], v[6:7], v[100:101]
	v_pk_fma_f32 v[8:9], v[8:9], v[14:15], v[98:99]
	v_lshl_add_u64 v[10:11], v[82:83], 0, v[90:91]
	v_cvt_pk_bf16_f32 v8, v8, v9
	v_cvt_pk_bf16_f32 v9, v6, v7
	flat_store_dwordx2 v[10:11], v[8:9]
	v_lshl_add_u64 v[6:7], v[2:3], 0, v[20:21]
	v_lshl_add_u64 v[14:15], v[0:1], 0, v[20:21]
	v_mov_b64_e32 v[6:7], v[186:187]
	v_mov_b64_e32 v[8:9], v[188:189]
	s_nop 0
	v_mov_b64_e32 v[98:99], v[198:199]
	v_mov_b64_e32 v[100:101], v[200:201]
	v_pk_add_f32 v[14:15], v[100:101], 1.0 op_sel_hi:[1,0]
	v_pk_add_f32 v[22:23], v[98:99], 1.0 op_sel_hi:[1,0]
	v_pk_fma_f32 v[8:9], v[30:31], v[14:15], v[8:9]
	v_pk_fma_f32 v[6:7], v[28:29], v[22:23], v[6:7]
	v_lshl_add_u64 v[14:15], v[0:1], 0, v[12:13]
	v_cvt_pk_bf16_f32 v6, v6, v7
	v_cvt_pk_bf16_f32 v7, v8, v9
	flat_store_dwordx2 v[10:11], v[6:7] offset:512
	v_lshl_add_u64 v[6:7], v[2:3], 0, v[12:13]
	v_mov_b64_e32 v[6:7], v[190:191]
	v_mov_b64_e32 v[8:9], v[192:193]
	v_lshl_add_u64 v[2:3], v[2:3], 0, v[4:5]
	v_mov_b64_e32 v[28:29], v[202:203]
	v_mov_b64_e32 v[30:31], v[204:205]
	v_lshl_add_u64 v[0:1], v[0:1], 0, v[4:5]
	v_pk_add_f32 v[14:15], v[30:31], 1.0 op_sel_hi:[1,0]
	v_pk_add_f32 v[22:23], v[28:29], 1.0 op_sel_hi:[1,0]
	v_pk_fma_f32 v[8:9], v[26:27], v[14:15], v[8:9]
	v_pk_fma_f32 v[6:7], v[24:25], v[22:23], v[6:7]
	s_nop 0
	v_cvt_pk_bf16_f32 v6, v6, v7
	v_cvt_pk_bf16_f32 v7, v8, v9
	flat_store_dwordx2 v[10:11], v[6:7] offset:1024
	v_mov_b64_e32 v[6:7], v[194:195]
	v_mov_b64_e32 v[8:9], v[196:197]
	s_nop 0
	v_mov_b64_e32 v[0:1], v[224:225]
	v_mov_b64_e32 v[2:3], v[226:227]
	v_pk_add_f32 v[2:3], v[2:3], 1.0 op_sel_hi:[1,0]
	v_pk_add_f32 v[0:1], v[0:1], 1.0 op_sel_hi:[1,0]
	v_pk_fma_f32 v[2:3], v[18:19], v[2:3], v[8:9]
	v_pk_fma_f32 v[0:1], v[16:17], v[0:1], v[6:7]
	v_lshl_add_u64 v[18:19], v[82:83], 0, v[94:95]
	v_cvt_pk_bf16_f32 v0, v0, v1
	v_cvt_pk_bf16_f32 v1, v2, v3
	flat_store_dwordx2 v[10:11], v[0:1] offset:1536
	v_lshl_add_u64 v[0:1], s[60:61], 0, v[92:93]
	v_lshl_add_u64 v[2:3], v[0:1], 0, s[4:5]
	v_lshl_add_u64 v[0:1], v[0:1], 0, s[8:9]
	v_lshl_add_u64 v[6:7], v[2:3], 0, v[152:153]
	v_lshl_add_u64 v[10:11], v[0:1], 0, v[152:153]
	global_load_dwordx4 v[186:189], v[6:7], off offset:1024
	global_load_dwordx4 v[190:193], v[6:7], off offset:2048
	global_load_dwordx4 v[194:197], v[6:7], off offset:3072
	flat_load_dwordx4 v[6:9], v[6:7]
	s_nop 0
	global_load_dwordx4 v[198:201], v[10:11], off offset:1024
	global_load_dwordx4 v[202:205], v[10:11], off offset:2048
	global_load_dwordx4 v[224:227], v[10:11], off offset:3072
	flat_load_dwordx4 v[14:17], v[10:11]
	s_waitcnt vmcnt(0) lgkmcnt(0)
	v_pk_add_f32 v[10:11], v[16:17], 1.0 op_sel_hi:[1,0]
	v_pk_add_f32 v[14:15], v[14:15], 1.0 op_sel_hi:[1,0]
	v_pk_fma_f32 v[8:9], v[62:63], v[10:11], v[8:9]
	v_pk_fma_f32 v[6:7], v[60:61], v[14:15], v[6:7]
	v_lshl_add_u64 v[10:11], v[82:83], 0, v[96:97]
	v_cvt_pk_bf16_f32 v6, v6, v7
	v_cvt_pk_bf16_f32 v7, v8, v9
	flat_store_dwordx2 v[10:11], v[6:7]
	v_lshl_add_u64 v[6:7], v[2:3], 0, v[20:21]
	v_lshl_add_u64 v[14:15], v[0:1], 0, v[20:21]
	v_mov_b64_e32 v[6:7], v[186:187]
	v_mov_b64_e32 v[8:9], v[188:189]
	s_nop 0
	v_mov_b64_e32 v[14:15], v[198:199]
	v_mov_b64_e32 v[16:17], v[200:201]
	v_pk_add_f32 v[16:17], v[16:17], 1.0 op_sel_hi:[1,0]
	v_pk_add_f32 v[14:15], v[14:15], 1.0 op_sel_hi:[1,0]
	v_pk_fma_f32 v[8:9], v[58:59], v[16:17], v[8:9]
	v_pk_fma_f32 v[6:7], v[56:57], v[14:15], v[6:7]
	v_lshl_add_u64 v[14:15], v[0:1], 0, v[12:13]
	v_cvt_pk_bf16_f32 v6, v6, v7
	v_cvt_pk_bf16_f32 v7, v8, v9
	flat_store_dwordx2 v[10:11], v[6:7] offset:512
	v_lshl_add_u64 v[6:7], v[2:3], 0, v[12:13]
	v_mov_b64_e32 v[6:7], v[190:191]
	v_mov_b64_e32 v[8:9], v[192:193]
	v_lshl_add_u64 v[2:3], v[2:3], 0, v[4:5]
	v_mov_b64_e32 v[14:15], v[202:203]
	v_mov_b64_e32 v[16:17], v[204:205]
	v_lshl_add_u64 v[0:1], v[0:1], 0, v[4:5]
	v_pk_add_f32 v[16:17], v[16:17], 1.0 op_sel_hi:[1,0]
	v_pk_add_f32 v[14:15], v[14:15], 1.0 op_sel_hi:[1,0]
	v_pk_fma_f32 v[8:9], v[54:55], v[16:17], v[8:9]
	v_pk_fma_f32 v[6:7], v[52:53], v[14:15], v[6:7]
	s_nop 0
	v_cvt_pk_bf16_f32 v6, v6, v7
	v_cvt_pk_bf16_f32 v7, v8, v9
	flat_store_dwordx2 v[10:11], v[6:7] offset:1024
	v_mov_b64_e32 v[6:7], v[194:195]
	v_mov_b64_e32 v[8:9], v[196:197]
	s_nop 0
	v_mov_b64_e32 v[0:1], v[224:225]
	v_mov_b64_e32 v[2:3], v[226:227]
	v_pk_add_f32 v[2:3], v[2:3], 1.0 op_sel_hi:[1,0]
	v_pk_add_f32 v[0:1], v[0:1], 1.0 op_sel_hi:[1,0]
	v_pk_fma_f32 v[2:3], v[50:51], v[2:3], v[8:9]
	v_pk_fma_f32 v[0:1], v[48:49], v[0:1], v[6:7]
	s_nop 0
	v_cvt_pk_bf16_f32 v0, v0, v1
	v_cvt_pk_bf16_f32 v1, v2, v3
	flat_store_dwordx2 v[10:11], v[0:1] offset:1536
	v_lshl_add_u64 v[0:1], s[60:61], 0, v[88:89]
	v_lshl_add_u64 v[2:3], v[0:1], 0, s[4:5]
	v_lshl_add_u64 v[0:1], v[0:1], 0, s[8:9]
	v_lshl_add_u64 v[6:7], v[2:3], 0, v[152:153]
	v_lshl_add_u64 v[10:11], v[0:1], 0, v[152:153]
	global_load_dwordx4 v[186:189], v[6:7], off offset:1024
	global_load_dwordx4 v[190:193], v[6:7], off offset:2048
	global_load_dwordx4 v[194:197], v[6:7], off offset:3072
	flat_load_dwordx4 v[6:9], v[6:7]
	s_nop 0
	global_load_dwordx4 v[198:201], v[10:11], off offset:1024
	global_load_dwordx4 v[202:205], v[10:11], off offset:2048
	global_load_dwordx4 v[224:227], v[10:11], off offset:3072
	flat_load_dwordx4 v[14:17], v[10:11]
	s_waitcnt vmcnt(0) lgkmcnt(0)
	v_pk_add_f32 v[10:11], v[16:17], 1.0 op_sel_hi:[1,0]
	v_pk_add_f32 v[14:15], v[14:15], 1.0 op_sel_hi:[1,0]
	v_pk_fma_f32 v[8:9], v[46:47], v[10:11], v[8:9]
	v_pk_fma_f32 v[6:7], v[44:45], v[14:15], v[6:7]
	v_lshl_add_u64 v[10:11], v[0:1], 0, v[20:21]
	v_cvt_pk_bf16_f32 v6, v6, v7
	v_cvt_pk_bf16_f32 v7, v8, v9
	flat_store_dwordx2 v[18:19], v[6:7]
	v_lshl_add_u64 v[6:7], v[2:3], 0, v[20:21]
	v_mov_b64_e32 v[6:7], v[186:187]
	v_mov_b64_e32 v[8:9], v[188:189]
	s_nop 0
	v_mov_b64_e32 v[14:15], v[198:199]
	v_mov_b64_e32 v[16:17], v[200:201]
	v_pk_add_f32 v[10:11], v[16:17], 1.0 op_sel_hi:[1,0]
	v_pk_add_f32 v[14:15], v[14:15], 1.0 op_sel_hi:[1,0]
	v_pk_fma_f32 v[8:9], v[42:43], v[10:11], v[8:9]
	v_pk_fma_f32 v[6:7], v[40:41], v[14:15], v[6:7]
	v_lshl_add_u64 v[10:11], v[0:1], 0, v[12:13]
	v_cvt_pk_bf16_f32 v6, v6, v7
	v_cvt_pk_bf16_f32 v7, v8, v9
	flat_store_dwordx2 v[18:19], v[6:7] offset:512
	v_lshl_add_u64 v[6:7], v[2:3], 0, v[12:13]
	v_mov_b64_e32 v[6:7], v[190:191]
	v_mov_b64_e32 v[8:9], v[192:193]
	v_lshl_add_u64 v[2:3], v[2:3], 0, v[4:5]
	v_mov_b64_e32 v[10:11], v[202:203]
	v_mov_b64_e32 v[12:13], v[204:205]
	v_lshl_add_u64 v[0:1], v[0:1], 0, v[4:5]
	v_pk_add_f32 v[12:13], v[12:13], 1.0 op_sel_hi:[1,0]
	v_pk_add_f32 v[10:11], v[10:11], 1.0 op_sel_hi:[1,0]
	v_pk_fma_f32 v[8:9], v[38:39], v[12:13], v[8:9]
	v_pk_fma_f32 v[6:7], v[36:37], v[10:11], v[6:7]
	s_nop 0
	v_cvt_pk_bf16_f32 v6, v6, v7
	v_cvt_pk_bf16_f32 v7, v8, v9
	flat_store_dwordx2 v[18:19], v[6:7] offset:1024
	v_mov_b64_e32 v[6:7], v[194:195]
	v_mov_b64_e32 v[8:9], v[196:197]
	s_nop 0
	v_mov_b64_e32 v[0:1], v[224:225]
	v_mov_b64_e32 v[2:3], v[226:227]
	v_pk_add_f32 v[2:3], v[2:3], 1.0 op_sel_hi:[1,0]
	v_pk_add_f32 v[0:1], v[0:1], 1.0 op_sel_hi:[1,0]
	v_pk_fma_f32 v[2:3], v[34:35], v[2:3], v[8:9]
	v_pk_fma_f32 v[0:1], v[32:33], v[0:1], v[6:7]
	s_nop 0
	v_cvt_pk_bf16_f32 v0, v0, v1
	v_cvt_pk_bf16_f32 v1, v2, v3
	flat_store_dwordx2 v[18:19], v[0:1] offset:1536
	s_branch .LBB0_50

.LBB0_225:
	global_load_dwordx4 v[154:157], v[74:75], off
	global_load_dwordx4 v[158:161], v[76:77], off
	global_load_dwordx4 v[162:165], v[74:75], off offset:1024
	global_load_dwordx4 v[166:169], v[76:77], off offset:1024
	global_load_dwordx4 v[170:173], v[74:75], off offset:2048
	global_load_dwordx4 v[174:177], v[76:77], off offset:2048
	global_load_dwordx4 v[178:181], v[74:75], off offset:3072
	global_load_dwordx4 v[182:185], v[76:77], off offset:3072
	v_add_u32_e32 v0, 0xfffff000, v64
	v_ashrrev_i32_e32 v0, 10, v0
	v_add_u32_e32 v0, 1, v0
	v_cmp_lt_i32_e32 vcc, s33, v64
	global_load_dwordx4 v[186:189], v[86:87], off offset:1024
	global_load_dwordx4 v[190:193], v[86:87], off offset:2048
	global_load_dwordx4 v[194:197], v[86:87], off offset:3072
	flat_load_dwordx4 v[8:11], v[86:87]
	s_mov_b64 s[8:9], 0x1000000
	v_cndmask_b32_e32 v94, 0, v0, vcc
	v_add_u32_e32 v0, s38, v64
	v_cmp_lt_i32_e32 vcc, s6, v0
	v_ashrrev_i32_e32 v95, 31, v94
	v_lshl_add_u64 v[4:5], v[94:95], 0, s[28:29]
	v_cndmask_b32_e32 v0, v0, v64, vcc
	v_add_u32_e32 v1, 0xfffff000, v0
	v_ashrrev_i32_e32 v1, 10, v1
	v_add_u32_e32 v1, 1, v1
	v_cmp_lt_i32_e32 vcc, s33, v0
	v_mad_u64_u32 v[2:3], s[4:5], v4, s7, v[78:79]
	s_nop 0
	v_cndmask_b32_e32 v92, 0, v1, vcc
	v_add_u32_e32 v1, s35, v64
	v_cmp_lt_i32_e32 vcc, s6, v1
	s_mov_b32 s4, 0x1000000
	v_mad_i32_i24 v3, v5, s7, v3
	v_cndmask_b32_e32 v18, v1, v64, vcc
	v_add_u32_e32 v1, 0xfffff000, v18
	v_ashrrev_i32_e32 v1, 10, v1
	v_add_u32_e32 v1, 1, v1
	v_cmp_lt_i32_e32 vcc, s33, v18
	global_load_dwordx4 v[198:201], v[2:3], off offset:1024
	global_load_dwordx4 v[202:205], v[2:3], off offset:2048
	global_load_dwordx4 v[224:227], v[2:3], off offset:3072
	flat_load_dwordx4 v[12:15], v[2:3]
	v_ashrrev_i32_e32 v93, 31, v92
	v_cndmask_b32_e32 v90, 0, v1, vcc
	v_add_u32_e32 v1, s26, v64
	v_cmp_lt_i32_e32 vcc, s6, v1
	v_lshlrev_b32_e32 v152, 1, v66
	v_lshlrev_b32_e32 v42, 1, v68
	v_cndmask_b32_e32 v16, v1, v64, vcc
	v_add_u32_e32 v1, 0xfffff000, v16
	v_ashrrev_i32_e32 v1, 10, v1
	v_add_u32_e32 v1, 1, v1
	v_cmp_lt_i32_e32 vcc, s33, v16
	v_mov_b32_e32 v43, v153
	v_lshlrev_b32_e32 v104, 1, v70
	v_cndmask_b32_e32 v88, 0, v1, vcc
	v_add_co_u32_e32 v4, vcc, s4, v84
	s_brev_b32 s4, 64
	s_nop 0
	v_addc_co_u32_e32 v5, vcc, 0, v85, vcc
	global_load_dwordx2 v[228:229], v[4:5], off offset:512
	global_load_dwordx2 v[230:231], v[4:5], off offset:1024
	global_load_dwordx2 v[232:233], v[4:5], off offset:1536
	flat_load_dwordx2 v[6:7], v[4:5]
	v_mov_b32_e32 v105, v153
	v_lshlrev_b32_e32 v106, 1, v72
	v_mov_b32_e32 v107, v153
	v_ashrrev_i32_e32 v19, 31, v18
	v_ashrrev_i32_e32 v91, 31, v90
	v_lshlrev_b64 v[100:101], 11, v[18:19]
	v_ashrrev_i32_e32 v17, 31, v16
	v_ashrrev_i32_e32 v89, 31, v88
	s_waitcnt vmcnt(0) lgkmcnt(0)
	v_pk_mul_f32 v[14:15], v[14:15], 0.5 op_sel_hi:[1,0]
	v_pk_mul_f32 v[12:13], v[12:13], 0.5 op_sel_hi:[1,0]
	v_lshlrev_b32_e32 v20, 16, v6
	v_and_b32_e32 v21, 0xffff0000, v6
	v_add_co_u32_e32 v6, vcc, s4, v84
	v_lshlrev_b32_e32 v22, 16, v7
	v_and_b32_e32 v23, 0xffff0000, v7
	v_addc_co_u32_e32 v7, vcc, 0, v85, vcc
	global_load_dwordx2 v[234:235], v[6:7], off offset:512
	global_load_dwordx2 v[236:237], v[6:7], off offset:1024
	global_load_dwordx2 v[238:239], v[6:7], off offset:1536
	flat_load_dwordx2 v[24:25], v[6:7]
	s_waitcnt vmcnt(0) lgkmcnt(0)
	v_lshlrev_b32_e32 v26, 16, v24
	v_and_b32_e32 v27, 0xffff0000, v24
	v_lshlrev_b32_e32 v24, 16, v25
	v_and_b32_e32 v25, 0xffff0000, v25
	v_pk_add_f32 v[20:21], v[20:21], v[26:27]
	v_pk_add_f32 v[22:23], v[22:23], v[24:25]
	v_pk_mul_f32 v[12:13], v[12:13], v[20:21]
	v_pk_mul_f32 v[14:15], v[14:15], v[22:23]
	v_pk_fma_f32 v[8:9], v[8:9], s[42:43], v[12:13] op_sel_hi:[1,0,1]
	v_pk_fma_f32 v[10:11], v[10:11], s[42:43], v[14:15] op_sel_hi:[1,0,1]
	v_mov_b32_e32 v14, v8
	v_pk_mov_b32 v[12:13], v[8:9], v[10:11] op_sel:[1,0]
	v_mov_b32_e32 v15, v11
	v_pk_add_f32 v[12:13], v[12:13], v[14:15]
	s_nop 0
	v_add_f32_e32 v1, v12, v13
	v_mov_b64_e32 v[12:13], v[186:187]
	v_mov_b64_e32 v[14:15], v[188:189]
	v_mov_b64_e32 v[20:21], v[198:199]
	v_mov_b64_e32 v[22:23], v[200:201]
	v_mov_b64_e32 v[24:25], v[228:229]
	v_mov_b64_e32 v[30:31], v[234:235]
	v_add_f32_e32 v28, 0, v1
	v_ashrrev_i32_e32 v1, 31, v0
	v_lshlrev_b64 v[96:97], 11, v[0:1]
	v_pk_mul_f32 v[22:23], v[22:23], 0.5 op_sel_hi:[1,0]
	v_lshlrev_b32_e32 v26, 16, v24
	v_and_b32_e32 v27, 0xffff0000, v24
	v_lshlrev_b32_e32 v24, 16, v25
	v_and_b32_e32 v25, 0xffff0000, v25
	v_lshlrev_b32_e32 v32, 16, v30
	v_and_b32_e32 v33, 0xffff0000, v30
	v_lshlrev_b32_e32 v30, 16, v31
	v_and_b32_e32 v31, 0xffff0000, v31
	v_pk_mul_f32 v[20:21], v[20:21], 0.5 op_sel_hi:[1,0]
	v_pk_add_f32 v[26:27], v[26:27], v[32:33]
	v_pk_add_f32 v[24:25], v[24:25], v[30:31]
	v_pk_mul_f32 v[20:21], v[20:21], v[26:27]
	v_pk_mul_f32 v[22:23], v[22:23], v[24:25]
	v_pk_fma_f32 v[12:13], v[12:13], s[42:43], v[20:21] op_sel_hi:[1,0,1]
	v_pk_fma_f32 v[14:15], v[14:15], s[42:43], v[22:23] op_sel_hi:[1,0,1]
	v_mov_b32_e32 v22, v12
	v_pk_mov_b32 v[20:21], v[12:13], v[14:15] op_sel:[1,0]
	v_mov_b32_e32 v23, v15
	v_pk_add_f32 v[20:21], v[20:21], v[22:23]
	s_nop 0
	v_pk_add_f32 v[30:31], v[20:21], v[20:21] op_sel:[0,1] op_sel_hi:[1,0]
	v_mov_b64_e32 v[20:21], v[190:191]
	v_mov_b64_e32 v[22:23], v[192:193]
	v_mov_b64_e32 v[24:25], v[202:203]
	v_mov_b64_e32 v[26:27], v[204:205]
	v_mov_b64_e32 v[32:33], v[230:231]
	v_mov_b64_e32 v[36:37], v[236:237]
	v_pk_mul_f32 v[26:27], v[26:27], 0.5 op_sel_hi:[1,0]
	v_lshlrev_b32_e32 v34, 16, v32
	v_and_b32_e32 v35, 0xffff0000, v32
	v_lshlrev_b32_e32 v32, 16, v33
	v_and_b32_e32 v33, 0xffff0000, v33
	v_lshlrev_b32_e32 v38, 16, v36
	v_and_b32_e32 v39, 0xffff0000, v36
	v_lshlrev_b32_e32 v36, 16, v37
	v_and_b32_e32 v37, 0xffff0000, v37
	v_pk_mul_f32 v[24:25], v[24:25], 0.5 op_sel_hi:[1,0]
	v_pk_add_f32 v[32:33], v[32:33], v[36:37]
	v_pk_add_f32 v[34:35], v[34:35], v[38:39]
	v_pk_mul_f32 v[26:27], v[26:27], v[32:33]
	v_pk_mul_f32 v[24:25], v[24:25], v[34:35]
	v_pk_fma_f32 v[22:23], v[22:23], s[42:43], v[26:27] op_sel_hi:[1,0,1]
	v_pk_fma_f32 v[20:21], v[20:21], s[42:43], v[24:25] op_sel_hi:[1,0,1]
	v_mov_b64_e32 v[24:25], v[194:195]
	v_mov_b64_e32 v[26:27], v[196:197]
	v_mov_b64_e32 v[32:33], v[224:225]
	v_mov_b64_e32 v[34:35], v[226:227]
	s_nop 0
	v_mov_b64_e32 v[2:3], v[232:233]
	v_add_f32_e32 v36, v20, v21
	v_mov_b64_e32 v[6:7], v[238:239]
	v_add_f32_e32 v38, v22, v23
	v_pk_mul_f32 v[34:35], v[34:35], 0.5 op_sel_hi:[1,0]
	v_lshlrev_b32_e32 v4, 16, v2
	v_and_b32_e32 v5, 0xffff0000, v2
	v_lshlrev_b32_e32 v2, 16, v3
	v_and_b32_e32 v3, 0xffff0000, v3
	v_lshlrev_b32_e32 v40, 16, v6
	v_and_b32_e32 v41, 0xffff0000, v6
	v_lshlrev_b32_e32 v6, 16, v7
	v_and_b32_e32 v7, 0xffff0000, v7
	v_pk_mul_f32 v[32:33], v[32:33], 0.5 op_sel_hi:[1,0]
	v_pk_add_f32 v[2:3], v[2:3], v[6:7]
	v_pk_add_f32 v[4:5], v[4:5], v[40:41]
	v_pk_mul_f32 v[2:3], v[34:35], v[2:3]
	v_pk_mul_f32 v[4:5], v[32:33], v[4:5]
	v_pk_fma_f32 v[26:27], v[26:27], s[42:43], v[2:3] op_sel_hi:[1,0,1]
	v_pk_fma_f32 v[24:25], v[24:25], s[42:43], v[4:5] op_sel_hi:[1,0,1]
	v_mov_b32_e32 v37, v26
	v_mov_b32_e32 v29, v24
	v_mov_b32_e32 v31, v25
	v_mov_b32_e32 v39, v27
	v_lshl_add_u64 v[34:35], s[56:57], 0, v[96:97]
	v_pk_add_f32 v[2:3], v[28:29], v[30:31]
	v_pk_add_f32 v[4:5], v[36:37], v[38:39]
	v_lshl_add_u64 v[6:7], v[92:93], 0, s[28:29]
	v_lshl_add_u64 v[46:47], v[34:35], 0, s[8:9]
	v_pk_add_f32 v[2:3], v[2:3], v[4:5]
	v_mad_u64_u32 v[4:5], s[4:5], v6, s7, v[78:79]
	v_lshl_add_u64 v[48:49], v[34:35], 0, v[152:153]
	v_lshl_add_u64 v[36:37], v[46:47], 0, v[152:153]
	v_mad_i32_i24 v5, v7, s7, v5
	global_load_dwordx2 v[228:229], v[48:49], off offset:512
	global_load_dwordx2 v[230:231], v[48:49], off offset:1024
	global_load_dwordx2 v[232:233], v[48:49], off offset:1536
	flat_load_dwordx2 v[6:7], v[48:49]
	v_add_f32_e32 v120, v2, v3
	global_load_dwordx2 v[234:235], v[36:37], off offset:512
	global_load_dwordx2 v[236:237], v[36:37], off offset:1024
	global_load_dwordx2 v[238:239], v[36:37], off offset:1536
	flat_load_dwordx2 v[36:37], v[36:37]
	v_lshlrev_b64 v[2:3], 12, v[0:1]
	global_load_dwordx4 v[186:189], v[4:5], off offset:1024
	global_load_dwordx4 v[190:193], v[4:5], off offset:2048
	global_load_dwordx4 v[194:197], v[4:5], off offset:3072
	flat_load_dwordx4 v[28:31], v[4:5]
	v_lshl_add_u64 v[32:33], v[80:81], 0, v[2:3]
	global_load_dwordx4 v[198:201], v[32:33], off offset:1024
	global_load_dwordx4 v[202:205], v[32:33], off offset:2048
	global_load_dwordx4 v[224:227], v[32:33], off offset:3072
	flat_load_dwordx4 v[0:3], v[32:33]
	v_lshl_add_u64 v[44:45], v[46:47], 0, v[42:43]
	v_lshl_add_u64 v[52:53], v[46:47], 0, v[104:105]
	v_lshl_add_u64 v[46:47], v[46:47], 0, v[106:107]
	s_waitcnt vmcnt(0) lgkmcnt(0)
	v_lshlrev_b32_e32 v34, 16, v6
	v_and_b32_e32 v35, 0xffff0000, v6
	v_lshlrev_b32_e32 v6, 16, v7
	v_and_b32_e32 v7, 0xffff0000, v7
	v_lshlrev_b32_e32 v38, 16, v36
	v_and_b32_e32 v39, 0xffff0000, v36
	v_lshlrev_b32_e32 v36, 16, v37
	v_and_b32_e32 v37, 0xffff0000, v37
	v_pk_mul_f32 v[30:31], v[30:31], 0.5 op_sel_hi:[1,0]
	v_pk_mul_f32 v[28:29], v[28:29], 0.5 op_sel_hi:[1,0]
	v_pk_add_f32 v[34:35], v[34:35], v[38:39]
	v_pk_add_f32 v[6:7], v[6:7], v[36:37]
	v_pk_mul_f32 v[28:29], v[28:29], v[34:35]
	v_pk_mul_f32 v[6:7], v[30:31], v[6:7]
	v_pk_fma_f32 v[34:35], v[0:1], s[42:43], v[28:29] op_sel_hi:[1,0,1]
	v_pk_fma_f32 v[36:37], v[2:3], s[42:43], v[6:7] op_sel_hi:[1,0,1]
	v_mov_b32_e32 v2, v34
	v_pk_mov_b32 v[0:1], v[34:35], v[36:37] op_sel:[1,0]
	v_mov_b32_e32 v3, v37
	v_pk_add_f32 v[0:1], v[0:1], v[2:3]
	s_nop 0
	v_add_f32_e32 v0, v0, v1
	v_add_f32_e32 v40, 0, v0
	v_mov_b64_e32 v[0:1], v[198:199]
	v_mov_b64_e32 v[2:3], v[200:201]
	v_mov_b64_e32 v[28:29], v[186:187]
	v_mov_b64_e32 v[30:31], v[188:189]
	v_mov_b64_e32 v[6:7], v[228:229]
	v_pk_mul_f32 v[30:31], v[30:31], 0.5 op_sel_hi:[1,0]
	v_mov_b64_e32 v[44:45], v[234:235]
	v_lshlrev_b32_e32 v38, 16, v6
	v_and_b32_e32 v39, 0xffff0000, v6
	v_lshlrev_b32_e32 v6, 16, v7
	v_and_b32_e32 v7, 0xffff0000, v7
	v_pk_mul_f32 v[28:29], v[28:29], 0.5 op_sel_hi:[1,0]
	v_lshlrev_b32_e32 v50, 16, v44
	v_and_b32_e32 v51, 0xffff0000, v44
	v_lshlrev_b32_e32 v44, 16, v45
	v_and_b32_e32 v45, 0xffff0000, v45
	v_pk_add_f32 v[38:39], v[38:39], v[50:51]
	v_pk_add_f32 v[6:7], v[6:7], v[44:45]
	v_pk_mul_f32 v[28:29], v[28:29], v[38:39]
	v_pk_mul_f32 v[6:7], v[30:31], v[6:7]
	v_pk_fma_f32 v[38:39], v[0:1], s[42:43], v[28:29] op_sel_hi:[1,0,1]
	v_pk_fma_f32 v[60:61], v[2:3], s[42:43], v[6:7] op_sel_hi:[1,0,1]
	v_mov_b32_e32 v2, v38
	v_pk_mov_b32 v[0:1], v[38:39], v[60:61] op_sel:[1,0]
	v_mov_b32_e32 v3, v61
	v_pk_add_f32 v[0:1], v[0:1], v[2:3]
	s_nop 0
	v_pk_add_f32 v[44:45], v[0:1], v[0:1] op_sel:[0,1] op_sel_hi:[1,0]
	v_mov_b64_e32 v[0:1], v[202:203]
	v_mov_b64_e32 v[2:3], v[204:205]
	v_mov_b64_e32 v[28:29], v[190:191]
	v_mov_b64_e32 v[30:31], v[192:193]
	v_mov_b64_e32 v[6:7], v[230:231]
	v_pk_mul_f32 v[30:31], v[30:31], 0.5 op_sel_hi:[1,0]
	v_mov_b64_e32 v[52:53], v[236:237]
	v_lshlrev_b32_e32 v50, 16, v6
	v_and_b32_e32 v51, 0xffff0000, v6
	v_lshlrev_b32_e32 v6, 16, v7
	v_and_b32_e32 v7, 0xffff0000, v7
	v_pk_mul_f32 v[28:29], v[28:29], 0.5 op_sel_hi:[1,0]
	v_lshlrev_b32_e32 v54, 16, v52
	v_and_b32_e32 v55, 0xffff0000, v52
	v_lshlrev_b32_e32 v52, 16, v53
	v_and_b32_e32 v53, 0xffff0000, v53
	v_pk_add_f32 v[6:7], v[6:7], v[52:53]
	v_pk_add_f32 v[50:51], v[50:51], v[54:55]
	v_pk_mul_f32 v[6:7], v[30:31], v[6:7]
	v_pk_mul_f32 v[28:29], v[28:29], v[50:51]
	v_pk_fma_f32 v[30:31], v[2:3], s[42:43], v[6:7] op_sel_hi:[1,0,1]
	v_pk_fma_f32 v[28:29], v[0:1], s[42:43], v[28:29] op_sel_hi:[1,0,1]
	v_mov_b64_e32 v[0:1], v[224:225]
	v_mov_b64_e32 v[2:3], v[226:227]
	s_nop 0
	v_mov_b64_e32 v[4:5], v[194:195]
	v_mov_b64_e32 v[6:7], v[196:197]
	s_nop 0
	v_mov_b64_e32 v[54:55], v[232:233]
	v_add_f32_e32 v50, v28, v29
	v_mov_b64_e32 v[46:47], v[238:239]
	v_add_f32_e32 v52, v30, v31
	v_pk_mul_f32 v[6:7], v[6:7], 0.5 op_sel_hi:[1,0]
	v_lshlrev_b32_e32 v48, 16, v54
	v_and_b32_e32 v49, 0xffff0000, v54
	v_lshlrev_b32_e32 v54, 16, v55
	v_and_b32_e32 v55, 0xffff0000, v55
	v_lshlrev_b32_e32 v56, 16, v46
	v_and_b32_e32 v57, 0xffff0000, v46
	v_lshlrev_b32_e32 v46, 16, v47
	v_and_b32_e32 v47, 0xffff0000, v47
	v_pk_mul_f32 v[4:5], v[4:5], 0.5 op_sel_hi:[1,0]
	v_pk_add_f32 v[46:47], v[54:55], v[46:47]
	v_pk_add_f32 v[48:49], v[48:49], v[56:57]
	v_pk_mul_f32 v[6:7], v[6:7], v[46:47]
	v_pk_mul_f32 v[4:5], v[4:5], v[48:49]
	v_pk_fma_f32 v[118:119], v[2:3], s[42:43], v[6:7] op_sel_hi:[1,0,1]
	v_pk_fma_f32 v[62:63], v[0:1], s[42:43], v[4:5] op_sel_hi:[1,0,1]
	v_mov_b32_e32 v51, v118
	v_mov_b32_e32 v41, v62
	v_mov_b32_e32 v45, v63
	v_mov_b32_e32 v53, v119
	v_pk_add_f32 v[0:1], v[40:41], v[44:45]
	v_pk_add_f32 v[2:3], v[50:51], v[52:53]
	v_lshl_add_u64 v[4:5], v[90:91], 0, s[28:29]
	v_pk_add_f32 v[0:1], v[0:1], v[2:3]
	v_mad_u64_u32 v[48:49], s[4:5], v4, s7, v[78:79]
	v_add_f32_e32 v121, v0, v1
	v_lshlrev_b64 v[0:1], 12, v[18:19]
	v_lshl_add_u64 v[18:19], s[56:57], 0, v[100:101]
	v_lshl_add_u64 v[46:47], v[18:19], 0, s[8:9]
	v_mad_i32_i24 v49, v5, s7, v49
	v_lshl_add_u64 v[18:19], v[18:19], 0, v[152:153]
	v_lshl_add_u64 v[52:53], v[46:47], 0, v[152:153]
	global_load_dwordx4 v[186:189], v[48:49], off offset:1024
	global_load_dwordx4 v[190:193], v[48:49], off offset:2048
	global_load_dwordx4 v[194:197], v[48:49], off offset:3072
	flat_load_dwordx4 v[4:7], v[48:49]
	global_load_dwordx2 v[228:229], v[18:19], off offset:512
	global_load_dwordx2 v[230:231], v[18:19], off offset:1024
	global_load_dwordx2 v[232:233], v[18:19], off offset:1536
	flat_load_dwordx2 v[44:45], v[18:19]
	v_lshl_add_u64 v[40:41], v[80:81], 0, v[0:1]
	global_load_dwordx2 v[234:235], v[52:53], off offset:512
	global_load_dwordx2 v[236:237], v[52:53], off offset:1024
	global_load_dwordx2 v[238:239], v[52:53], off offset:1536
	flat_load_dwordx2 v[52:53], v[52:53]
	v_lshl_add_u64 v[56:57], v[46:47], 0, v[42:43]
	global_load_dwordx4 v[198:201], v[40:41], off offset:1024
	global_load_dwordx4 v[202:205], v[40:41], off offset:2048
	global_load_dwordx4 v[224:227], v[40:41], off offset:3072
	flat_load_dwordx4 v[0:3], v[40:41]
	v_lshl_add_u64 v[108:109], v[46:47], 0, v[104:105]
	v_lshl_add_u64 v[46:47], v[46:47], 0, v[106:107]
	s_waitcnt vmcnt(0) lgkmcnt(0)
	v_pk_mul_f32 v[6:7], v[6:7], 0.5 op_sel_hi:[1,0]
	v_lshlrev_b32_e32 v50, 16, v44
	v_and_b32_e32 v51, 0xffff0000, v44
	v_lshlrev_b32_e32 v44, 16, v45
	v_and_b32_e32 v45, 0xffff0000, v45
	v_lshlrev_b32_e32 v54, 16, v52
	v_and_b32_e32 v55, 0xffff0000, v52
	v_lshlrev_b32_e32 v52, 16, v53
	v_and_b32_e32 v53, 0xffff0000, v53
	v_pk_mul_f32 v[4:5], v[4:5], 0.5 op_sel_hi:[1,0]
	v_pk_add_f32 v[50:51], v[50:51], v[54:55]
	v_pk_add_f32 v[44:45], v[44:45], v[52:53]
	v_pk_mul_f32 v[4:5], v[4:5], v[50:51]
	v_pk_mul_f32 v[6:7], v[6:7], v[44:45]
	v_pk_fma_f32 v[44:45], v[0:1], s[42:43], v[4:5] op_sel_hi:[1,0,1]
	v_pk_fma_f32 v[50:51], v[2:3], s[42:43], v[6:7] op_sel_hi:[1,0,1]
	v_mov_b32_e32 v2, v44
	v_pk_mov_b32 v[0:1], v[44:45], v[50:51] op_sel:[1,0]
	v_mov_b32_e32 v3, v51
	v_pk_add_f32 v[0:1], v[0:1], v[2:3]
	s_nop 0
	v_add_f32_e32 v0, v0, v1
	v_add_f32_e32 v98, 0, v0
	v_mov_b64_e32 v[0:1], v[198:199]
	v_mov_b64_e32 v[2:3], v[200:201]
	v_mov_b64_e32 v[4:5], v[186:187]
	v_mov_b64_e32 v[6:7], v[188:189]
	v_mov_b64_e32 v[52:53], v[228:229]
	v_pk_mul_f32 v[6:7], v[6:7], 0.5 op_sel_hi:[1,0]
	v_mov_b64_e32 v[56:57], v[234:235]
	v_lshlrev_b32_e32 v54, 16, v52
	v_and_b32_e32 v55, 0xffff0000, v52
	v_lshlrev_b32_e32 v52, 16, v53
	v_and_b32_e32 v53, 0xffff0000, v53
	v_pk_mul_f32 v[4:5], v[4:5], 0.5 op_sel_hi:[1,0]
	v_lshlrev_b32_e32 v58, 16, v56
	v_and_b32_e32 v59, 0xffff0000, v56
	v_lshlrev_b32_e32 v56, 16, v57
	v_and_b32_e32 v57, 0xffff0000, v57
	v_pk_add_f32 v[54:55], v[54:55], v[58:59]
	v_pk_add_f32 v[52:53], v[52:53], v[56:57]
	v_pk_mul_f32 v[4:5], v[4:5], v[54:55]
	v_pk_mul_f32 v[6:7], v[6:7], v[52:53]
	v_pk_fma_f32 v[56:57], v[0:1], s[42:43], v[4:5] op_sel_hi:[1,0,1]
	v_pk_fma_f32 v[58:59], v[2:3], s[42:43], v[6:7] op_sel_hi:[1,0,1]
	v_mov_b32_e32 v2, v56
	v_pk_mov_b32 v[0:1], v[56:57], v[58:59] op_sel:[1,0]
	v_mov_b32_e32 v3, v59
	v_pk_add_f32 v[0:1], v[0:1], v[2:3]
	s_nop 0
	v_pk_add_f32 v[102:103], v[0:1], v[0:1] op_sel:[0,1] op_sel_hi:[1,0]
	v_mov_b64_e32 v[0:1], v[202:203]
	v_mov_b64_e32 v[2:3], v[204:205]
	v_mov_b64_e32 v[4:5], v[190:191]
	v_mov_b64_e32 v[6:7], v[192:193]
	v_mov_b64_e32 v[52:53], v[230:231]
	v_pk_mul_f32 v[6:7], v[6:7], 0.5 op_sel_hi:[1,0]
	v_mov_b64_e32 v[108:109], v[236:237]
	v_lshlrev_b32_e32 v54, 16, v52
	v_and_b32_e32 v55, 0xffff0000, v52
	v_lshlrev_b32_e32 v52, 16, v53
	v_and_b32_e32 v53, 0xffff0000, v53
	v_pk_mul_f32 v[4:5], v[4:5], 0.5 op_sel_hi:[1,0]
	v_lshlrev_b32_e32 v110, 16, v108
	v_and_b32_e32 v111, 0xffff0000, v108
	v_lshlrev_b32_e32 v108, 16, v109
	v_and_b32_e32 v109, 0xffff0000, v109
	v_pk_add_f32 v[52:53], v[52:53], v[108:109]
	v_pk_add_f32 v[54:55], v[54:55], v[110:111]
	v_pk_mul_f32 v[6:7], v[6:7], v[52:53]
	v_pk_mul_f32 v[4:5], v[4:5], v[54:55]
	v_pk_fma_f32 v[54:55], v[2:3], s[42:43], v[6:7] op_sel_hi:[1,0,1]
	v_pk_fma_f32 v[52:53], v[0:1], s[42:43], v[4:5] op_sel_hi:[1,0,1]
	v_mov_b64_e32 v[0:1], v[224:225]
	v_mov_b64_e32 v[2:3], v[226:227]
	v_mov_b64_e32 v[4:5], v[194:195]
	v_mov_b64_e32 v[6:7], v[196:197]
	s_nop 0
	v_mov_b64_e32 v[18:19], v[232:233]
	v_add_f32_e32 v108, v52, v53
	v_mov_b64_e32 v[46:47], v[238:239]
	v_add_f32_e32 v110, v54, v55
	v_pk_mul_f32 v[6:7], v[6:7], 0.5 op_sel_hi:[1,0]
	v_lshlrev_b32_e32 v48, 16, v18
	v_and_b32_e32 v49, 0xffff0000, v18
	v_lshlrev_b32_e32 v18, 16, v19
	v_and_b32_e32 v19, 0xffff0000, v19
	v_lshlrev_b32_e32 v112, 16, v46
	v_and_b32_e32 v113, 0xffff0000, v46
	v_lshlrev_b32_e32 v46, 16, v47
	v_and_b32_e32 v47, 0xffff0000, v47
	v_pk_mul_f32 v[4:5], v[4:5], 0.5 op_sel_hi:[1,0]
	v_pk_add_f32 v[18:19], v[18:19], v[46:47]
	v_pk_add_f32 v[46:47], v[48:49], v[112:113]
	v_pk_mul_f32 v[6:7], v[6:7], v[18:19]
	v_pk_mul_f32 v[4:5], v[4:5], v[46:47]
	v_pk_fma_f32 v[48:49], v[2:3], s[42:43], v[6:7] op_sel_hi:[1,0,1]
	v_pk_fma_f32 v[46:47], v[0:1], s[42:43], v[4:5] op_sel_hi:[1,0,1]
	v_mov_b32_e32 v109, v48
	v_mov_b32_e32 v99, v46
	v_mov_b32_e32 v103, v47
	v_mov_b32_e32 v111, v49
	v_pk_add_f32 v[0:1], v[98:99], v[102:103]
	v_pk_add_f32 v[2:3], v[108:109], v[110:111]
	v_lshlrev_b64 v[98:99], 11, v[16:17]
	v_pk_add_f32 v[0:1], v[0:1], v[2:3]
	v_lshl_add_u64 v[4:5], v[88:89], 0, s[28:29]
	v_add_f32_e32 v125, v0, v1
	v_lshlrev_b64 v[0:1], 12, v[16:17]
	v_lshl_add_u64 v[16:17], s[56:57], 0, v[98:99]
	v_lshl_add_u64 v[18:19], v[16:17], 0, s[8:9]
	v_mad_u64_u32 v[126:127], s[4:5], v4, s7, v[78:79]
	v_mad_i32_i24 v127, v5, s7, v127
	v_lshl_add_u64 v[16:17], v[16:17], 0, v[152:153]
	v_lshl_add_u64 v[112:113], v[18:19], 0, v[152:153]
	global_load_dwordx4 v[186:189], v[126:127], off offset:1024
	global_load_dwordx4 v[190:193], v[126:127], off offset:2048
	global_load_dwordx4 v[194:197], v[126:127], off offset:3072
	flat_load_dwordx4 v[4:7], v[126:127]
	global_load_dwordx2 v[228:229], v[16:17], off offset:512
	global_load_dwordx2 v[230:231], v[16:17], off offset:1024
	global_load_dwordx2 v[232:233], v[16:17], off offset:1536
	flat_load_dwordx2 v[108:109], v[16:17]
	v_lshl_add_u64 v[102:103], v[80:81], 0, v[0:1]
	global_load_dwordx2 v[234:235], v[112:113], off offset:512
	global_load_dwordx2 v[236:237], v[112:113], off offset:1024
	global_load_dwordx2 v[238:239], v[112:113], off offset:1536
	flat_load_dwordx2 v[112:113], v[112:113]
	v_lshl_add_u64 v[42:43], v[18:19], 0, v[42:43]
	global_load_dwordx4 v[198:201], v[102:103], off offset:1024
	global_load_dwordx4 v[202:205], v[102:103], off offset:2048
	global_load_dwordx4 v[224:227], v[102:103], off offset:3072
	flat_load_dwordx4 v[0:3], v[102:103]
	v_lshl_add_u64 v[104:105], v[18:19], 0, v[104:105]
	v_lshl_add_u64 v[18:19], v[18:19], 0, v[106:107]
	s_mov_b32 s4, 0x3727c5ac
	s_waitcnt vmcnt(0) lgkmcnt(0)
	v_pk_mul_f32 v[6:7], v[6:7], 0.5 op_sel_hi:[1,0]
	v_lshlrev_b32_e32 v110, 16, v108
	v_and_b32_e32 v111, 0xffff0000, v108
	v_lshlrev_b32_e32 v108, 16, v109
	v_and_b32_e32 v109, 0xffff0000, v109
	v_lshlrev_b32_e32 v114, 16, v112
	v_and_b32_e32 v115, 0xffff0000, v112
	v_lshlrev_b32_e32 v112, 16, v113
	v_and_b32_e32 v113, 0xffff0000, v113
	v_pk_mul_f32 v[4:5], v[4:5], 0.5 op_sel_hi:[1,0]
	v_pk_add_f32 v[110:111], v[110:111], v[114:115]
	v_pk_add_f32 v[108:109], v[108:109], v[112:113]
	v_pk_mul_f32 v[4:5], v[4:5], v[110:111]
	v_pk_mul_f32 v[6:7], v[6:7], v[108:109]
	v_pk_fma_f32 v[114:115], v[0:1], s[42:43], v[4:5] op_sel_hi:[1,0,1]
	v_pk_fma_f32 v[116:117], v[2:3], s[42:43], v[6:7] op_sel_hi:[1,0,1]
	v_mov_b32_e32 v2, v114
	v_pk_mov_b32 v[0:1], v[114:115], v[116:117] op_sel:[1,0]
	v_mov_b32_e32 v3, v117
	v_pk_add_f32 v[0:1], v[0:1], v[2:3]
	s_nop 0
	v_add_f32_e32 v0, v0, v1
	v_add_f32_e32 v128, 0, v0
	v_mov_b64_e32 v[0:1], v[198:199]
	v_mov_b64_e32 v[2:3], v[200:201]
	v_mov_b64_e32 v[4:5], v[186:187]
	v_mov_b64_e32 v[6:7], v[188:189]
	v_mov_b64_e32 v[108:109], v[228:229]
	v_pk_mul_f32 v[6:7], v[6:7], 0.5 op_sel_hi:[1,0]
	v_mov_b64_e32 v[42:43], v[234:235]
	v_lshlrev_b32_e32 v110, 16, v108
	v_and_b32_e32 v111, 0xffff0000, v108
	v_lshlrev_b32_e32 v108, 16, v109
	v_and_b32_e32 v109, 0xffff0000, v109
	v_pk_mul_f32 v[4:5], v[4:5], 0.5 op_sel_hi:[1,0]
	v_lshlrev_b32_e32 v112, 16, v42
	v_and_b32_e32 v113, 0xffff0000, v42
	v_lshlrev_b32_e32 v42, 16, v43
	v_and_b32_e32 v43, 0xffff0000, v43
	v_pk_add_f32 v[110:111], v[110:111], v[112:113]
	v_pk_add_f32 v[42:43], v[108:109], v[42:43]
	v_pk_mul_f32 v[4:5], v[4:5], v[110:111]
	v_pk_mul_f32 v[6:7], v[6:7], v[42:43]
	v_pk_fma_f32 v[42:43], v[0:1], s[42:43], v[4:5] op_sel_hi:[1,0,1]
	v_pk_fma_f32 v[112:113], v[2:3], s[42:43], v[6:7] op_sel_hi:[1,0,1]
	v_mov_b32_e32 v2, v42
	v_pk_mov_b32 v[0:1], v[42:43], v[112:113] op_sel:[1,0]
	v_mov_b32_e32 v3, v113
	v_pk_add_f32 v[0:1], v[0:1], v[2:3]
	s_nop 0
	v_pk_add_f32 v[130:131], v[0:1], v[0:1] op_sel:[0,1] op_sel_hi:[1,0]
	v_mov_b64_e32 v[0:1], v[202:203]
	v_mov_b64_e32 v[2:3], v[204:205]
	v_mov_b64_e32 v[4:5], v[190:191]
	v_mov_b64_e32 v[6:7], v[192:193]
	v_mov_b64_e32 v[108:109], v[230:231]
	v_pk_mul_f32 v[6:7], v[6:7], 0.5 op_sel_hi:[1,0]
	v_mov_b64_e32 v[104:105], v[236:237]
	v_lshlrev_b32_e32 v110, 16, v108
	v_and_b32_e32 v111, 0xffff0000, v108
	v_lshlrev_b32_e32 v108, 16, v109
	v_and_b32_e32 v109, 0xffff0000, v109
	v_pk_mul_f32 v[4:5], v[4:5], 0.5 op_sel_hi:[1,0]
	v_lshlrev_b32_e32 v132, 16, v104
	v_and_b32_e32 v133, 0xffff0000, v104
	v_lshlrev_b32_e32 v104, 16, v105
	v_and_b32_e32 v105, 0xffff0000, v105
	v_pk_add_f32 v[104:105], v[108:109], v[104:105]
	v_pk_add_f32 v[108:109], v[110:111], v[132:133]
	v_pk_mul_f32 v[6:7], v[6:7], v[104:105]
	v_pk_mul_f32 v[4:5], v[4:5], v[108:109]
	v_pk_fma_f32 v[110:111], v[2:3], s[42:43], v[6:7] op_sel_hi:[1,0,1]
	v_pk_fma_f32 v[108:109], v[0:1], s[42:43], v[4:5] op_sel_hi:[1,0,1]
	v_mov_b64_e32 v[0:1], v[224:225]
	v_mov_b64_e32 v[2:3], v[226:227]
	v_mov_b64_e32 v[4:5], v[194:195]
	v_mov_b64_e32 v[6:7], v[196:197]
	s_nop 0
	v_mov_b64_e32 v[16:17], v[232:233]
	v_add_f32_e32 v132, v108, v109
	v_mov_b64_e32 v[18:19], v[238:239]
	v_add_f32_e32 v134, v110, v111
	v_pk_mul_f32 v[6:7], v[6:7], 0.5 op_sel_hi:[1,0]
	v_lshlrev_b32_e32 v104, 16, v16
	v_and_b32_e32 v105, 0xffff0000, v16
	v_lshlrev_b32_e32 v16, 16, v17
	v_and_b32_e32 v17, 0xffff0000, v17
	v_lshlrev_b32_e32 v106, 16, v18
	v_and_b32_e32 v107, 0xffff0000, v18
	v_lshlrev_b32_e32 v18, 16, v19
	v_and_b32_e32 v19, 0xffff0000, v19
	v_pk_mul_f32 v[4:5], v[4:5], 0.5 op_sel_hi:[1,0]
	v_pk_add_f32 v[16:17], v[16:17], v[18:19]
	v_pk_add_f32 v[18:19], v[104:105], v[106:107]
	v_pk_mul_f32 v[6:7], v[6:7], v[16:17]
	v_pk_mul_f32 v[4:5], v[4:5], v[18:19]
	v_pk_fma_f32 v[106:107], v[2:3], s[42:43], v[6:7] op_sel_hi:[1,0,1]
	v_pk_fma_f32 v[104:105], v[0:1], s[42:43], v[4:5] op_sel_hi:[1,0,1]
	v_mov_b32_e32 v133, v106
	v_mov_b32_e32 v129, v104
	v_mov_b32_e32 v131, v105
	v_mov_b32_e32 v135, v107
	v_pk_add_f32 v[0:1], v[128:129], v[130:131]
	v_pk_add_f32 v[2:3], v[132:133], v[134:135]
	ds_bpermute_b32 v18, v67, v121
	v_pk_add_f32 v[0:1], v[0:1], v[2:3]
	s_waitcnt lgkmcnt(0)
	v_add_f32_e32 v18, v121, v18
	v_add_f32_e32 v65, v0, v1
	ds_bpermute_b32 v0, v67, v120
	ds_bpermute_b32 v19, v69, v18
	s_waitcnt lgkmcnt(1)
	v_add_f32_e32 v0, v120, v0
	ds_bpermute_b32 v1, v69, v0
	s_waitcnt lgkmcnt(1)
	v_add_f32_e32 v18, v18, v19
	ds_bpermute_b32 v19, v71, v18
	s_waitcnt lgkmcnt(1)
	v_add_f32_e32 v0, v0, v1
	ds_bpermute_b32 v1, v71, v0
	s_waitcnt lgkmcnt(1)
	v_add_f32_e32 v18, v18, v19
	ds_bpermute_b32 v19, v73, v18
	s_waitcnt lgkmcnt(1)
	v_add_f32_e32 v0, v0, v1
	ds_bpermute_b32 v1, v73, v0
	s_waitcnt lgkmcnt(1)
	v_add_f32_e32 v18, v18, v19
	ds_bpermute_b32 v19, v123, v18
	s_waitcnt lgkmcnt(1)
	v_add_f32_e32 v0, v0, v1
	ds_bpermute_b32 v1, v123, v0
	s_waitcnt lgkmcnt(1)
	v_add_f32_e32 v18, v18, v19
	ds_bpermute_b32 v19, v124, v18
	s_waitcnt lgkmcnt(1)
	v_add_f32_e32 v0, v0, v1
	ds_bpermute_b32 v1, v124, v0
	s_waitcnt lgkmcnt(1)
	v_add_f32_e32 v122, v18, v19
	v_fmamk_f32 v35, v122, 0xba800000, v35
	v_fmac_f32_e32 v34, 0xba800000, v122
	v_fmamk_f32 v37, v122, 0xba800000, v37
	s_waitcnt lgkmcnt(0)
	v_add_f32_e32 v16, v0, v1
	v_fmamk_f32 v9, v16, 0xba800000, v9
	v_fmac_f32_e32 v8, 0xba800000, v16
	v_fmamk_f32 v11, v16, 0xba800000, v11
	v_fmac_f32_e32 v10, 0xba800000, v16
	v_pk_mul_f32 v[0:1], v[10:11], v[10:11]
	v_pk_mul_f32 v[2:3], v[8:9], v[8:9]
	v_fmamk_f32 v13, v16, 0xba800000, v13
	v_pk_mov_b32 v[4:5], v[2:3], v[0:1] op_sel:[1,0]
	v_mov_b32_e32 v3, v1
	v_pk_add_f32 v[0:1], v[4:5], v[2:3]
	v_fmac_f32_e32 v12, 0xba800000, v16
	v_fmamk_f32 v15, v16, 0xba800000, v15
	v_fmac_f32_e32 v14, 0xba800000, v16
	v_pk_add_f32 v[0:1], v[0:1], v[0:1] op_sel_hi:[0,1]
	v_pk_mul_f32 v[2:3], v[14:15], v[14:15]
	v_pk_mul_f32 v[4:5], v[12:13], v[12:13]
	v_fmac_f32_e32 v20, 0xba800000, v16
	v_pk_mov_b32 v[6:7], v[4:5], v[2:3] op_sel:[1,0]
	v_mov_b32_e32 v5, v3
	v_fmamk_f32 v21, v16, 0xba800000, v21
	v_fmac_f32_e32 v22, 0xba800000, v16
	v_mul_f32_e32 v0, v20, v20
	v_pk_add_f32 v[2:3], v[6:7], v[4:5]
	v_fmamk_f32 v23, v16, 0xba800000, v23
	v_pk_fma_f32 v[4:5], v[20:21], v[20:21], v[0:1] op_sel_hi:[1,1,0]
	v_mul_f32_e32 v0, v22, v22
	v_pk_add_f32 v[2:3], v[2:3], v[2:3] op_sel_hi:[0,1]
	v_pk_fma_f32 v[6:7], v[22:23], v[22:23], v[0:1] op_sel_hi:[1,1,0]
	v_fmamk_f32 v27, v16, 0xba800000, v27
	v_fmac_f32_e32 v26, 0xba800000, v16
	v_fmamk_f32 v25, v16, 0xba800000, v25
	v_fmac_f32_e32 v24, 0xba800000, v16
	v_mul_f32_e32 v4, v24, v24
	v_mul_f32_e32 v6, v25, v25
	v_mul_f32_e32 v0, v26, v26
	v_mul_f32_e32 v2, v27, v27
	v_pk_add_f32 v[4:5], v[4:5], v[6:7]
	v_pk_add_f32 v[0:1], v[0:1], v[2:3]
	v_fmac_f32_e32 v36, 0xba800000, v122
	v_pk_add_f32 v[16:17], v[4:5], v[0:1]
	v_mov_b64_e32 v[0:1], v[154:155]
	v_mov_b64_e32 v[2:3], v[156:157]
	v_mov_b64_e32 v[4:5], v[158:159]
	v_mov_b64_e32 v[6:7], v[160:161]
	v_pk_mul_f32 v[18:19], v[36:37], v[36:37]
	v_pk_mul_f32 v[120:121], v[34:35], v[34:35]
	v_fmamk_f32 v39, v122, 0xba800000, v39
	v_pk_mov_b32 v[126:127], v[120:121], v[18:19] op_sel:[1,0]
	v_mov_b32_e32 v121, v19
	v_pk_add_f32 v[18:19], v[126:127], v[120:121]
	v_fmac_f32_e32 v38, 0xba800000, v122
	v_fmamk_f32 v61, v122, 0xba800000, v61
	v_fmac_f32_e32 v60, 0xba800000, v122
	v_pk_add_f32 v[18:19], v[18:19], v[18:19] op_sel_hi:[0,1]
	v_pk_mul_f32 v[120:121], v[60:61], v[60:61]
	v_pk_mul_f32 v[126:127], v[38:39], v[38:39]
	v_fmac_f32_e32 v28, 0xba800000, v122
	v_pk_mov_b32 v[128:129], v[126:127], v[120:121] op_sel:[1,0]
	v_mov_b32_e32 v127, v121
	v_fmamk_f32 v29, v122, 0xba800000, v29
	v_fmac_f32_e32 v30, 0xba800000, v122
	v_mul_f32_e32 v18, v28, v28
	v_pk_add_f32 v[120:121], v[128:129], v[126:127]
	v_fmamk_f32 v31, v122, 0xba800000, v31
	v_pk_fma_f32 v[126:127], v[28:29], v[28:29], v[18:19] op_sel_hi:[1,1,0]
	v_mul_f32_e32 v18, v30, v30
	v_pk_add_f32 v[120:121], v[120:121], v[120:121] op_sel_hi:[0,1]
	v_pk_fma_f32 v[128:129], v[30:31], v[30:31], v[18:19] op_sel_hi:[1,1,0]
	v_fmamk_f32 v119, v122, 0xba800000, v119
	v_fmac_f32_e32 v118, 0xba800000, v122
	v_fmamk_f32 v63, v122, 0xba800000, v63
	v_fmac_f32_e32 v62, 0xba800000, v122
	v_mul_f32_e32 v126, v62, v62
	v_mul_f32_e32 v128, v63, v63
	v_mul_f32_e32 v18, v118, v118
	v_mul_f32_e32 v120, v119, v119
	v_pk_add_f32 v[126:127], v[126:127], v[128:129]
	v_pk_add_f32 v[18:19], v[18:19], v[120:121]
	v_mov_b32_e32 v121, v16
	v_pk_add_f32 v[18:19], v[126:127], v[18:19]
	s_nop 0
	v_mov_b32_e32 v120, v18
	v_mov_b32_e32 v16, v19
	v_pk_add_f32 v[16:17], v[120:121], v[16:17]
	ds_bpermute_b32 v19, v67, v17
	ds_bpermute_b32 v18, v67, v16
	v_mov_b64_e32 v[120:121], s[4:5]
	s_mov_b32 s4, 0x3a800000
	s_waitcnt lgkmcnt(0)
	v_pk_add_f32 v[16:17], v[16:17], v[18:19]
	ds_bpermute_b32 v19, v69, v17
	ds_bpermute_b32 v18, v69, v16
	s_waitcnt lgkmcnt(0)
	v_pk_add_f32 v[16:17], v[16:17], v[18:19]
	ds_bpermute_b32 v19, v71, v17
	ds_bpermute_b32 v18, v71, v16
	s_waitcnt lgkmcnt(0)
	v_pk_add_f32 v[16:17], v[16:17], v[18:19]
	ds_bpermute_b32 v19, v73, v17
	ds_bpermute_b32 v18, v73, v16
	s_waitcnt lgkmcnt(0)
	v_pk_add_f32 v[16:17], v[16:17], v[18:19]
	ds_bpermute_b32 v19, v123, v17
	ds_bpermute_b32 v18, v123, v16
	s_waitcnt lgkmcnt(0)
	v_pk_add_f32 v[16:17], v[16:17], v[18:19]
	ds_bpermute_b32 v19, v124, v17
	ds_bpermute_b32 v18, v124, v16
	s_waitcnt lgkmcnt(0)
	v_pk_add_f32 v[16:17], v[16:17], v[18:19]
	s_nop 0
	v_pk_fma_f32 v[126:127], v[16:17], s[4:5], v[120:121] op_sel_hi:[1,0,0]
	s_nop 0
	v_mul_f32_e32 v16, 0x4b800000, v127
	v_cmp_gt_f32_e64 s[8:9], s68, v127
	v_cmp_gt_f32_e32 vcc, s68, v126
	s_nop 0
	v_cndmask_b32_e64 v16, v127, v16, s[8:9]
	v_rsq_f32_e32 v16, v16
	s_nop 0
	v_mul_f32_e32 v17, 0x45800000, v16
	v_cndmask_b32_e64 v122, v16, v17, s[8:9]
	v_pk_mul_f32 v[8:9], v[8:9], v[122:123] op_sel_hi:[1,0]
	v_pk_mul_f32 v[10:11], v[10:11], v[122:123] op_sel_hi:[1,0]
	v_pk_fma_f32 v[16:17], v[0:1], v[8:9], v[4:5]
	v_pk_fma_f32 v[18:19], v[2:3], v[10:11], v[6:7]
	flat_store_dwordx4 v[86:87], v[16:19]
	v_mov_b64_e32 v[0:1], v[162:163]
	v_mov_b64_e32 v[2:3], v[164:165]
	v_mov_b64_e32 v[4:5], v[166:167]
	v_mov_b64_e32 v[6:7], v[168:169]
	v_pk_mul_f32 v[8:9], v[14:15], v[122:123] op_sel_hi:[1,0]
	v_pk_mul_f32 v[10:11], v[12:13], v[122:123] op_sel_hi:[1,0]
	v_pk_fma_f32 v[14:15], v[2:3], v[8:9], v[6:7]
	v_pk_fma_f32 v[12:13], v[0:1], v[10:11], v[4:5]
	flat_store_dwordx4 v[86:87], v[12:15] offset:1024
	v_mov_b64_e32 v[0:1], v[170:171]
	v_mov_b64_e32 v[2:3], v[172:173]
	v_mov_b64_e32 v[4:5], v[174:175]
	v_mov_b64_e32 v[6:7], v[176:177]
	v_pk_mul_f32 v[8:9], v[22:23], v[122:123] op_sel_hi:[1,0]
	v_pk_mul_f32 v[10:11], v[20:21], v[122:123] op_sel_hi:[1,0]
	v_pk_mul_f32 v[22:23], v[24:25], v[122:123] op_sel_hi:[1,0]
	v_pk_mul_f32 v[20:21], v[26:27], v[122:123] op_sel_hi:[1,0]
	v_pk_fma_f32 v[4:5], v[0:1], v[10:11], v[4:5]
	v_pk_fma_f32 v[6:7], v[2:3], v[8:9], v[6:7]
	flat_store_dwordx4 v[86:87], v[4:7] offset:2048
	v_mov_b64_e32 v[0:1], v[178:179]
	v_mov_b64_e32 v[2:3], v[180:181]
	v_mov_b64_e32 v[8:9], v[182:183]
	v_mov_b64_e32 v[10:11], v[184:185]
	v_pk_fma_f32 v[0:1], v[0:1], v[22:23], v[8:9]
	v_mul_f32_e32 v8, 0x4b800000, v126
	v_cndmask_b32_e32 v8, v126, v8, vcc
	v_rsq_f32_e32 v8, v8
	v_pk_fma_f32 v[2:3], v[2:3], v[20:21], v[10:11]
	flat_store_dwordx4 v[86:87], v[0:3] offset:3072
	v_mul_f32_e32 v9, 0x45800000, v8
	v_cndmask_b32_e32 v122, v8, v9, vcc
	v_mov_b64_e32 v[8:9], v[154:155]
	v_mov_b64_e32 v[10:11], v[156:157]
	v_mov_b64_e32 v[20:21], v[158:159]
	v_mov_b64_e32 v[22:23], v[160:161]
	v_pk_mul_f32 v[24:25], v[36:37], v[122:123] op_sel_hi:[1,0]
	v_pk_mul_f32 v[26:27], v[34:35], v[122:123] op_sel_hi:[1,0]
	v_pk_mul_f32 v[34:35], v[60:61], v[122:123] op_sel_hi:[1,0]
	v_pk_mul_f32 v[36:37], v[38:39], v[122:123] op_sel_hi:[1,0]
	v_pk_mul_f32 v[38:39], v[118:119], v[122:123] op_sel_hi:[1,0]
	v_pk_mul_f32 v[60:61], v[62:63], v[122:123] op_sel_hi:[1,0]
	ds_bpermute_b32 v62, v67, v65
	s_waitcnt lgkmcnt(0)
	v_add_f32_e32 v62, v65, v62
	ds_bpermute_b32 v63, v69, v62
	s_waitcnt lgkmcnt(0)
	v_add_f32_e32 v62, v62, v63
	ds_bpermute_b32 v63, v71, v62
	s_waitcnt lgkmcnt(0)
	v_add_f32_e32 v62, v62, v63
	ds_bpermute_b32 v63, v73, v62
	s_waitcnt lgkmcnt(0)
	v_add_f32_e32 v62, v62, v63
	ds_bpermute_b32 v63, v123, v62
	s_waitcnt lgkmcnt(0)
	v_add_f32_e32 v62, v62, v63
	ds_bpermute_b32 v63, v124, v62
	s_waitcnt lgkmcnt(0)
	v_add_f32_e32 v65, v62, v63
	v_fmamk_f32 v115, v65, 0xba800000, v115
	v_fmac_f32_e32 v114, 0xba800000, v65
	v_fmamk_f32 v117, v65, 0xba800000, v117
	v_fmac_f32_e32 v116, 0xba800000, v65
	v_pk_mul_f32 v[62:63], v[116:117], v[116:117]
	v_pk_mul_f32 v[118:119], v[114:115], v[114:115]
	v_fmamk_f32 v43, v65, 0xba800000, v43
	v_pk_mov_b32 v[126:127], v[118:119], v[62:63] op_sel:[1,0]
	v_mov_b32_e32 v119, v63
	v_pk_add_f32 v[62:63], v[126:127], v[118:119]
	v_fmac_f32_e32 v42, 0xba800000, v65
	v_fmamk_f32 v113, v65, 0xba800000, v113
	v_fmac_f32_e32 v112, 0xba800000, v65
	v_pk_add_f32 v[62:63], v[62:63], v[62:63] op_sel_hi:[0,1]
	v_pk_mul_f32 v[118:119], v[112:113], v[112:113]
	v_pk_mul_f32 v[126:127], v[42:43], v[42:43]
	v_fmac_f32_e32 v108, 0xba800000, v65
	v_pk_mov_b32 v[128:129], v[126:127], v[118:119] op_sel:[1,0]
	v_mov_b32_e32 v127, v119
	v_fmamk_f32 v109, v65, 0xba800000, v109
	v_fmac_f32_e32 v110, 0xba800000, v65
	v_mul_f32_e32 v62, v108, v108
	v_pk_add_f32 v[118:119], v[128:129], v[126:127]
	v_fmamk_f32 v111, v65, 0xba800000, v111
	v_pk_fma_f32 v[126:127], v[108:109], v[108:109], v[62:63] op_sel_hi:[1,1,0]
	v_mul_f32_e32 v62, v110, v110
	v_pk_add_f32 v[118:119], v[118:119], v[118:119] op_sel_hi:[0,1]
	v_pk_fma_f32 v[128:129], v[110:111], v[110:111], v[62:63] op_sel_hi:[1,1,0]
	v_fmamk_f32 v107, v65, 0xba800000, v107
	v_fmac_f32_e32 v106, 0xba800000, v65
	v_fmamk_f32 v105, v65, 0xba800000, v105
	v_fmac_f32_e32 v104, 0xba800000, v65
	v_mul_f32_e32 v126, v104, v104
	v_mul_f32_e32 v128, v105, v105
	v_mul_f32_e32 v62, v106, v106
	v_mul_f32_e32 v118, v107, v107
	v_pk_add_f32 v[126:127], v[126:127], v[128:129]
	v_pk_fma_f32 v[8:9], v[8:9], v[26:27], v[20:21]
	v_pk_fma_f32 v[10:11], v[10:11], v[24:25], v[22:23]
	flat_store_dwordx4 v[32:33], v[8:11]
	v_mov_b64_e32 v[20:21], v[162:163]
	v_mov_b64_e32 v[22:23], v[164:165]
	v_mov_b64_e32 v[24:25], v[166:167]
	v_mov_b64_e32 v[26:27], v[168:169]
	v_pk_add_f32 v[62:63], v[62:63], v[118:119]
	v_pk_fma_f32 v[20:21], v[20:21], v[36:37], v[24:25]
	v_pk_fma_f32 v[22:23], v[22:23], v[34:35], v[26:27]
	flat_store_dwordx4 v[32:33], v[20:23] offset:1024
	v_pk_mul_f32 v[34:35], v[30:31], v[122:123] op_sel_hi:[1,0]
	v_pk_mul_f32 v[36:37], v[28:29], v[122:123] op_sel_hi:[1,0]
	v_mov_b64_e32 v[24:25], v[170:171]
	v_mov_b64_e32 v[26:27], v[172:173]
	v_mov_b64_e32 v[28:29], v[174:175]
	v_mov_b64_e32 v[30:31], v[176:177]
	v_pk_add_f32 v[62:63], v[126:127], v[62:63]
	v_pk_fma_f32 v[28:29], v[24:25], v[36:37], v[28:29]
	v_pk_fma_f32 v[30:31], v[26:27], v[34:35], v[30:31]
	flat_store_dwordx4 v[32:33], v[28:31] offset:2048
	v_mov_b64_e32 v[24:25], v[178:179]
	v_mov_b64_e32 v[26:27], v[180:181]
	v_mov_b64_e32 v[34:35], v[182:183]
	v_mov_b64_e32 v[36:37], v[184:185]
	v_mov_b32_e32 v118, v62
	v_pk_fma_f32 v[24:25], v[24:25], v[60:61], v[34:35]
	v_pk_fma_f32 v[26:27], v[26:27], v[38:39], v[36:37]
	flat_store_dwordx4 v[32:33], v[24:27] offset:3072
	ds_bpermute_b32 v32, v67, v125
	s_waitcnt lgkmcnt(0)
	v_add_f32_e32 v32, v125, v32
	ds_bpermute_b32 v33, v69, v32
	s_waitcnt lgkmcnt(0)
	v_add_f32_e32 v32, v32, v33
	ds_bpermute_b32 v33, v71, v32
	s_waitcnt lgkmcnt(0)
	v_add_f32_e32 v32, v32, v33
	ds_bpermute_b32 v33, v73, v32
	s_waitcnt lgkmcnt(0)
	v_add_f32_e32 v32, v32, v33
	ds_bpermute_b32 v33, v123, v32
	s_waitcnt lgkmcnt(0)
	v_add_f32_e32 v32, v32, v33
	ds_bpermute_b32 v33, v124, v32
	s_waitcnt lgkmcnt(0)
	v_add_f32_e32 v60, v32, v33
	v_fmamk_f32 v45, v60, 0xba800000, v45
	v_fmac_f32_e32 v44, 0xba800000, v60
	v_fmamk_f32 v51, v60, 0xba800000, v51
	v_fmac_f32_e32 v50, 0xba800000, v60
	v_pk_mul_f32 v[32:33], v[50:51], v[50:51]
	v_pk_mul_f32 v[34:35], v[44:45], v[44:45]
	v_fmamk_f32 v57, v60, 0xba800000, v57
	v_pk_mov_b32 v[36:37], v[34:35], v[32:33] op_sel:[1,0]
	v_mov_b32_e32 v35, v33
	v_pk_add_f32 v[32:33], v[36:37], v[34:35]
	v_fmac_f32_e32 v56, 0xba800000, v60
	v_fmamk_f32 v59, v60, 0xba800000, v59
	v_fmac_f32_e32 v58, 0xba800000, v60
	v_pk_add_f32 v[32:33], v[32:33], v[32:33] op_sel_hi:[0,1]
	v_pk_mul_f32 v[34:35], v[58:59], v[58:59]
	v_pk_mul_f32 v[36:37], v[56:57], v[56:57]
	v_fmac_f32_e32 v52, 0xba800000, v60
	v_pk_mov_b32 v[38:39], v[36:37], v[34:35] op_sel:[1,0]
	v_mov_b32_e32 v37, v35
	v_fmamk_f32 v53, v60, 0xba800000, v53
	v_fmac_f32_e32 v54, 0xba800000, v60
	v_mul_f32_e32 v32, v52, v52
	v_pk_add_f32 v[34:35], v[38:39], v[36:37]
	v_fmamk_f32 v55, v60, 0xba800000, v55
	v_pk_fma_f32 v[36:37], v[52:53], v[52:53], v[32:33] op_sel_hi:[1,1,0]
	v_mul_f32_e32 v32, v54, v54
	v_pk_add_f32 v[34:35], v[34:35], v[34:35] op_sel_hi:[0,1]
	v_pk_fma_f32 v[38:39], v[54:55], v[54:55], v[32:33] op_sel_hi:[1,1,0]
	v_fmamk_f32 v49, v60, 0xba800000, v49
	v_fmac_f32_e32 v48, 0xba800000, v60
	v_fmamk_f32 v47, v60, 0xba800000, v47
	v_fmac_f32_e32 v46, 0xba800000, v60
	v_mul_f32_e32 v36, v46, v46
	v_mul_f32_e32 v38, v47, v47
	v_mul_f32_e32 v32, v48, v48
	v_mul_f32_e32 v34, v49, v49
	v_pk_add_f32 v[36:37], v[36:37], v[38:39]
	v_pk_add_f32 v[32:33], v[32:33], v[34:35]
	s_nop 0
	v_pk_add_f32 v[60:61], v[36:37], v[32:33]
	v_mov_b64_e32 v[32:33], v[154:155]
	v_mov_b64_e32 v[34:35], v[156:157]
	v_mov_b64_e32 v[36:37], v[158:159]
	v_mov_b64_e32 v[38:39], v[160:161]
	v_mov_b32_e32 v119, v60
	v_mov_b32_e32 v60, v63
	v_pk_add_f32 v[60:61], v[118:119], v[60:61]
	ds_bpermute_b32 v63, v67, v61
	ds_bpermute_b32 v62, v67, v60
	s_waitcnt lgkmcnt(0)
	v_pk_add_f32 v[60:61], v[60:61], v[62:63]
	ds_bpermute_b32 v63, v69, v61
	ds_bpermute_b32 v62, v69, v60
	s_waitcnt lgkmcnt(0)
	v_pk_add_f32 v[60:61], v[60:61], v[62:63]
	ds_bpermute_b32 v63, v71, v61
	ds_bpermute_b32 v62, v71, v60
	s_waitcnt lgkmcnt(0)
	v_pk_add_f32 v[60:61], v[60:61], v[62:63]
	ds_bpermute_b32 v63, v73, v61
	ds_bpermute_b32 v62, v73, v60
	s_waitcnt lgkmcnt(0)
	v_pk_add_f32 v[60:61], v[60:61], v[62:63]
	ds_bpermute_b32 v63, v123, v61
	ds_bpermute_b32 v62, v123, v60
	s_waitcnt lgkmcnt(0)
	v_pk_add_f32 v[60:61], v[60:61], v[62:63]
	ds_bpermute_b32 v63, v124, v61
	ds_bpermute_b32 v62, v124, v60
	s_waitcnt lgkmcnt(0)
	v_pk_add_f32 v[60:61], v[60:61], v[62:63]
	s_nop 0
	v_pk_fma_f32 v[118:119], v[60:61], s[4:5], v[120:121] op_sel_hi:[1,0,0]
	s_nop 0
	v_mul_f32_e32 v60, 0x4b800000, v119
	v_cmp_gt_f32_e64 s[8:9], s68, v119
	v_cmp_gt_f32_e32 vcc, s68, v118
	s_nop 0
	v_cndmask_b32_e64 v60, v119, v60, s[8:9]
	v_rsq_f32_e32 v60, v60
	s_nop 0
	v_mul_f32_e32 v61, 0x45800000, v60
	v_cndmask_b32_e64 v120, v60, v61, s[8:9]
	v_pk_mul_f32 v[50:51], v[50:51], v[120:121] op_sel_hi:[1,0]
	v_pk_mul_f32 v[44:45], v[44:45], v[120:121] op_sel_hi:[1,0]
	v_pk_mul_f32 v[46:47], v[46:47], v[120:121] op_sel_hi:[1,0]
	v_pk_fma_f32 v[60:61], v[32:33], v[44:45], v[36:37]
	v_pk_fma_f32 v[62:63], v[34:35], v[50:51], v[38:39]
	flat_store_dwordx4 v[40:41], v[60:63]
	v_mov_b64_e32 v[32:33], v[162:163]
	v_mov_b64_e32 v[34:35], v[164:165]
	v_mov_b64_e32 v[36:37], v[166:167]
	v_mov_b64_e32 v[38:39], v[168:169]
	v_pk_mul_f32 v[44:45], v[58:59], v[120:121] op_sel_hi:[1,0]
	v_pk_mul_f32 v[50:51], v[56:57], v[120:121] op_sel_hi:[1,0]
	v_pk_fma_f32 v[58:59], v[34:35], v[44:45], v[38:39]
	v_pk_fma_f32 v[56:57], v[32:33], v[50:51], v[36:37]
	flat_store_dwordx4 v[40:41], v[56:59] offset:1024
	v_mov_b64_e32 v[32:33], v[170:171]
	v_mov_b64_e32 v[34:35], v[172:173]
	v_mov_b64_e32 v[36:37], v[174:175]
	v_mov_b64_e32 v[38:39], v[176:177]
	v_pk_mul_f32 v[44:45], v[54:55], v[120:121] op_sel_hi:[1,0]
	v_pk_mul_f32 v[50:51], v[52:53], v[120:121] op_sel_hi:[1,0]
	v_pk_fma_f32 v[54:55], v[34:35], v[44:45], v[38:39]
	v_pk_fma_f32 v[52:53], v[32:33], v[50:51], v[36:37]
	flat_store_dwordx4 v[40:41], v[52:55] offset:2048
	v_mov_b64_e32 v[32:33], v[178:179]
	v_mov_b64_e32 v[34:35], v[180:181]
	v_mov_b64_e32 v[36:37], v[182:183]
	v_mov_b64_e32 v[38:39], v[184:185]
	v_pk_mul_f32 v[44:45], v[48:49], v[120:121] op_sel_hi:[1,0]
	v_pk_fma_f32 v[48:49], v[32:33], v[46:47], v[36:37]
	v_mul_f32_e32 v32, 0x4b800000, v118
	v_cndmask_b32_e32 v32, v118, v32, vcc
	v_rsq_f32_e32 v32, v32
	v_pk_fma_f32 v[50:51], v[34:35], v[44:45], v[38:39]
	flat_store_dwordx4 v[40:41], v[48:51] offset:3072
	v_mul_f32_e32 v33, 0x45800000, v32
	v_cndmask_b32_e32 v118, v32, v33, vcc
	v_mov_b64_e32 v[32:33], v[154:155]
	v_mov_b64_e32 v[34:35], v[156:157]
	v_mov_b64_e32 v[36:37], v[158:159]
	v_mov_b64_e32 v[38:39], v[160:161]
	v_pk_mul_f32 v[40:41], v[116:117], v[118:119] op_sel_hi:[1,0]
	v_pk_mul_f32 v[44:45], v[114:115], v[118:119] op_sel_hi:[1,0]
	v_pk_mul_f32 v[112:113], v[112:113], v[118:119] op_sel_hi:[1,0]
	v_pk_mul_f32 v[110:111], v[110:111], v[118:119] op_sel_hi:[1,0]
	v_pk_mul_f32 v[108:109], v[108:109], v[118:119] op_sel_hi:[1,0]
	s_andn2_b64 vcc, exec, s[14:15]
	v_pk_fma_f32 v[44:45], v[32:33], v[44:45], v[36:37]
	v_pk_fma_f32 v[46:47], v[34:35], v[40:41], v[38:39]
	flat_store_dwordx4 v[102:103], v[44:47]
	v_mov_b64_e32 v[32:33], v[162:163]
	v_mov_b64_e32 v[34:35], v[164:165]
	v_mov_b64_e32 v[36:37], v[166:167]
	v_mov_b64_e32 v[38:39], v[168:169]
	v_pk_mul_f32 v[40:41], v[42:43], v[118:119] op_sel_hi:[1,0]
	v_pk_fma_f32 v[42:43], v[34:35], v[112:113], v[38:39]
	v_pk_fma_f32 v[40:41], v[32:33], v[40:41], v[36:37]
	flat_store_dwordx4 v[102:103], v[40:43] offset:1024
	v_mov_b64_e32 v[32:33], v[170:171]
	v_mov_b64_e32 v[34:35], v[172:173]
	v_mov_b64_e32 v[36:37], v[174:175]
	v_mov_b64_e32 v[38:39], v[176:177]
	v_pk_fma_f32 v[36:37], v[32:33], v[108:109], v[36:37]
	v_pk_fma_f32 v[38:39], v[34:35], v[110:111], v[38:39]
	flat_store_dwordx4 v[102:103], v[36:39] offset:2048
	v_pk_mul_f32 v[108:109], v[106:107], v[118:119] op_sel_hi:[1,0]
	v_pk_mul_f32 v[110:111], v[104:105], v[118:119] op_sel_hi:[1,0]
	v_mov_b64_e32 v[32:33], v[178:179]
	v_mov_b64_e32 v[34:35], v[180:181]
	v_mov_b64_e32 v[104:105], v[182:183]
	v_mov_b64_e32 v[106:107], v[184:185]
	v_pk_fma_f32 v[32:33], v[32:33], v[110:111], v[104:105]
	v_pk_fma_f32 v[34:35], v[34:35], v[108:109], v[106:107]
	flat_store_dwordx4 v[102:103], v[32:35] offset:3072
	s_cbranch_vccnz .LBB0_224
	v_lshl_add_u64 v[102:103], v[94:95], 0, s[2:3]
	v_mov_b64_e32 v[94:95], s[60:61]
	v_mad_u64_u32 v[104:105], s[4:5], v102, s7, v[94:95]
	v_mad_i32_i24 v105, v103, s7, v105
	v_lshl_add_u64 v[110:111], v[104:105], 0, s[30:31]
	v_lshlrev_b32_e32 v152, 2, v66
	v_lshl_add_u64 v[112:113], v[104:105], 0, v[152:153]
	v_lshl_add_u64 v[106:107], v[110:111], 0, v[152:153]
	global_load_dwordx4 v[186:189], v[112:113], off offset:1024
	global_load_dwordx4 v[190:193], v[112:113], off offset:2048
	global_load_dwordx4 v[194:197], v[112:113], off offset:3072
	flat_load_dwordx4 v[102:105], v[112:113]
	s_nop 0
	global_load_dwordx4 v[198:201], v[106:107], off offset:1024
	global_load_dwordx4 v[202:205], v[106:107], off offset:2048
	global_load_dwordx4 v[224:227], v[106:107], off offset:3072
	flat_load_dwordx4 v[106:109], v[106:107]
	s_waitcnt vmcnt(0) lgkmcnt(0)
	v_pk_add_f32 v[108:109], v[108:109], 1.0 op_sel_hi:[1,0]
	v_pk_add_f32 v[106:107], v[106:107], 1.0 op_sel_hi:[1,0]
	v_pk_fma_f32 v[18:19], v[18:19], v[108:109], v[104:105]
	v_pk_fma_f32 v[16:17], v[16:17], v[106:107], v[102:103]
	s_nop 0
	v_cvt_pk_bf16_f32 v16, v16, v17
	v_cvt_pk_bf16_f32 v17, v18, v19
	flat_store_dwordx2 v[84:85], v[16:17]
	v_lshlrev_b32_e32 v16, 2, v68
	v_mov_b32_e32 v17, v153
	v_lshl_add_u64 v[18:19], v[110:111], 0, v[16:17]
	v_mov_b64_e32 v[102:103], v[186:187]
	v_mov_b64_e32 v[104:105], v[188:189]
	v_mov_b64_e32 v[106:107], v[198:199]
	v_mov_b64_e32 v[108:109], v[200:201]
	v_pk_add_f32 v[18:19], v[108:109], 1.0 op_sel_hi:[1,0]
	v_pk_add_f32 v[106:107], v[106:107], 1.0 op_sel_hi:[1,0]
	v_pk_fma_f32 v[14:15], v[14:15], v[18:19], v[104:105]
	v_pk_fma_f32 v[12:13], v[12:13], v[106:107], v[102:103]
	s_nop 0
	v_cvt_pk_bf16_f32 v12, v12, v13
	v_cvt_pk_bf16_f32 v13, v14, v15
	flat_store_dwordx2 v[84:85], v[12:13] offset:512
	v_lshlrev_b32_e32 v12, 2, v70
	v_mov_b32_e32 v13, v153
	v_lshl_add_u64 v[14:15], v[110:111], 0, v[12:13]
	v_mov_b64_e32 v[102:103], v[190:191]
	v_mov_b64_e32 v[104:105], v[192:193]
	v_mov_b64_e32 v[106:107], v[202:203]
	v_mov_b64_e32 v[108:109], v[204:205]
	v_pk_add_f32 v[14:15], v[108:109], 1.0 op_sel_hi:[1,0]
	v_pk_add_f32 v[18:19], v[106:107], 1.0 op_sel_hi:[1,0]
	v_pk_fma_f32 v[6:7], v[6:7], v[14:15], v[104:105]
	v_pk_fma_f32 v[4:5], v[4:5], v[18:19], v[102:103]
	s_nop 0
	v_cvt_pk_bf16_f32 v4, v4, v5
	v_cvt_pk_bf16_f32 v5, v6, v7
	flat_store_dwordx2 v[84:85], v[4:5] offset:1024
	v_lshlrev_b32_e32 v4, 2, v72
	v_mov_b32_e32 v5, v153
	v_lshl_add_u64 v[6:7], v[110:111], 0, v[4:5]
	v_mov_b64_e32 v[102:103], v[194:195]
	v_mov_b64_e32 v[104:105], v[196:197]
	v_mov_b64_e32 v[106:107], v[224:225]
	v_mov_b64_e32 v[108:109], v[226:227]
	v_pk_add_f32 v[6:7], v[108:109], 1.0 op_sel_hi:[1,0]
	v_pk_add_f32 v[14:15], v[106:107], 1.0 op_sel_hi:[1,0]
	v_pk_fma_f32 v[2:3], v[2:3], v[6:7], v[104:105]
	v_pk_fma_f32 v[0:1], v[0:1], v[14:15], v[102:103]
	s_nop 0
	v_cvt_pk_bf16_f32 v0, v0, v1
	v_cvt_pk_bf16_f32 v1, v2, v3
	flat_store_dwordx2 v[84:85], v[0:1] offset:1536
	v_lshl_add_u64 v[0:1], v[92:93], 0, s[2:3]
	v_mad_u64_u32 v[2:3], s[4:5], v0, s7, v[94:95]
	v_mad_i32_i24 v3, v1, s7, v3
	v_lshl_add_u64 v[0:1], v[2:3], 0, s[30:31]
	v_lshl_add_u64 v[2:3], v[2:3], 0, v[152:153]
	v_lshl_add_u64 v[6:7], v[0:1], 0, v[152:153]
	global_load_dwordx4 v[186:189], v[2:3], off offset:1024
	global_load_dwordx4 v[190:193], v[2:3], off offset:2048
	global_load_dwordx4 v[194:197], v[2:3], off offset:3072
	flat_load_dwordx4 v[102:105], v[2:3]
	global_load_dwordx4 v[198:201], v[6:7], off offset:1024
	global_load_dwordx4 v[202:205], v[6:7], off offset:2048
	global_load_dwordx4 v[224:227], v[6:7], off offset:3072
	flat_load_dwordx4 v[106:109], v[6:7]
	s_waitcnt vmcnt(0) lgkmcnt(0)
	v_pk_add_f32 v[6:7], v[108:109], 1.0 op_sel_hi:[1,0]
	v_pk_add_f32 v[14:15], v[106:107], 1.0 op_sel_hi:[1,0]
	v_pk_fma_f32 v[6:7], v[10:11], v[6:7], v[104:105]
	v_pk_fma_f32 v[8:9], v[8:9], v[14:15], v[102:103]
	v_lshl_add_u64 v[10:11], v[82:83], 0, v[96:97]
	v_cvt_pk_bf16_f32 v8, v8, v9
	v_cvt_pk_bf16_f32 v9, v6, v7
	flat_store_dwordx2 v[10:11], v[8:9]
	v_lshl_add_u64 v[14:15], v[0:1], 0, v[16:17]
	v_mov_b64_e32 v[6:7], v[186:187]
	v_mov_b64_e32 v[8:9], v[188:189]
	v_mov_b64_e32 v[102:103], v[198:199]
	v_mov_b64_e32 v[104:105], v[200:201]
	v_pk_add_f32 v[14:15], v[104:105], 1.0 op_sel_hi:[1,0]
	v_pk_add_f32 v[18:19], v[102:103], 1.0 op_sel_hi:[1,0]
	v_pk_fma_f32 v[8:9], v[22:23], v[14:15], v[8:9]
	v_pk_fma_f32 v[6:7], v[20:21], v[18:19], v[6:7]
	v_lshl_add_u64 v[14:15], v[0:1], 0, v[12:13]
	v_cvt_pk_bf16_f32 v6, v6, v7
	v_cvt_pk_bf16_f32 v7, v8, v9
	flat_store_dwordx2 v[10:11], v[6:7] offset:512
	v_mov_b64_e32 v[6:7], v[190:191]
	v_mov_b64_e32 v[8:9], v[192:193]
	v_lshl_add_u64 v[0:1], v[0:1], 0, v[4:5]
	v_mov_b64_e32 v[18:19], v[202:203]
	v_mov_b64_e32 v[20:21], v[204:205]
	v_pk_add_f32 v[14:15], v[20:21], 1.0 op_sel_hi:[1,0]
	v_pk_add_f32 v[18:19], v[18:19], 1.0 op_sel_hi:[1,0]
	v_pk_fma_f32 v[8:9], v[30:31], v[14:15], v[8:9]
	v_pk_fma_f32 v[6:7], v[28:29], v[18:19], v[6:7]
	s_nop 0
	v_cvt_pk_bf16_f32 v6, v6, v7
	v_cvt_pk_bf16_f32 v7, v8, v9
	flat_store_dwordx2 v[10:11], v[6:7] offset:1024
	v_mov_b64_e32 v[6:7], v[194:195]
	v_mov_b64_e32 v[8:9], v[196:197]
	s_nop 0
	v_mov_b64_e32 v[0:1], v[224:225]
	v_mov_b64_e32 v[2:3], v[226:227]
	v_pk_add_f32 v[2:3], v[2:3], 1.0 op_sel_hi:[1,0]
	v_pk_add_f32 v[0:1], v[0:1], 1.0 op_sel_hi:[1,0]
	v_pk_fma_f32 v[2:3], v[26:27], v[2:3], v[8:9]
	v_pk_fma_f32 v[0:1], v[24:25], v[0:1], v[6:7]
	s_nop 0
	v_cvt_pk_bf16_f32 v0, v0, v1
	v_cvt_pk_bf16_f32 v1, v2, v3
	flat_store_dwordx2 v[10:11], v[0:1] offset:1536
	v_lshl_add_u64 v[0:1], v[90:91], 0, s[2:3]
	v_mad_u64_u32 v[2:3], s[4:5], v0, s7, v[94:95]
	v_mad_i32_i24 v3, v1, s7, v3
	v_lshl_add_u64 v[0:1], v[2:3], 0, s[30:31]
	v_lshl_add_u64 v[2:3], v[2:3], 0, v[152:153]
	v_lshl_add_u64 v[10:11], v[0:1], 0, v[152:153]
	global_load_dwordx4 v[186:189], v[2:3], off offset:1024
	global_load_dwordx4 v[190:193], v[2:3], off offset:2048
	global_load_dwordx4 v[194:197], v[2:3], off offset:3072
	flat_load_dwordx4 v[6:9], v[2:3]
	global_load_dwordx4 v[198:201], v[10:11], off offset:1024
	global_load_dwordx4 v[202:205], v[10:11], off offset:2048
	global_load_dwordx4 v[224:227], v[10:11], off offset:3072
	flat_load_dwordx4 v[18:21], v[10:11]
	s_waitcnt vmcnt(0) lgkmcnt(0)
	v_pk_add_f32 v[10:11], v[20:21], 1.0 op_sel_hi:[1,0]
	v_pk_add_f32 v[14:15], v[18:19], 1.0 op_sel_hi:[1,0]
	v_pk_fma_f32 v[8:9], v[62:63], v[10:11], v[8:9]
	v_pk_fma_f32 v[6:7], v[60:61], v[14:15], v[6:7]
	v_lshl_add_u64 v[10:11], v[82:83], 0, v[100:101]
	v_cvt_pk_bf16_f32 v6, v6, v7
	v_cvt_pk_bf16_f32 v7, v8, v9
	flat_store_dwordx2 v[10:11], v[6:7]
	v_lshl_add_u64 v[14:15], v[0:1], 0, v[16:17]
	v_mov_b64_e32 v[6:7], v[186:187]
	v_mov_b64_e32 v[8:9], v[188:189]
	v_mov_b64_e32 v[18:19], v[198:199]
	v_mov_b64_e32 v[20:21], v[200:201]
	v_pk_add_f32 v[14:15], v[20:21], 1.0 op_sel_hi:[1,0]
	v_pk_add_f32 v[18:19], v[18:19], 1.0 op_sel_hi:[1,0]
	v_pk_fma_f32 v[8:9], v[58:59], v[14:15], v[8:9]
	v_pk_fma_f32 v[6:7], v[56:57], v[18:19], v[6:7]
	v_lshl_add_u64 v[14:15], v[0:1], 0, v[12:13]
	v_cvt_pk_bf16_f32 v6, v6, v7
	v_cvt_pk_bf16_f32 v7, v8, v9
	flat_store_dwordx2 v[10:11], v[6:7] offset:512
	v_mov_b64_e32 v[6:7], v[190:191]
	v_mov_b64_e32 v[8:9], v[192:193]
	v_lshl_add_u64 v[0:1], v[0:1], 0, v[4:5]
	v_mov_b64_e32 v[18:19], v[202:203]
	v_mov_b64_e32 v[20:21], v[204:205]
	v_pk_add_f32 v[14:15], v[20:21], 1.0 op_sel_hi:[1,0]
	v_pk_add_f32 v[18:19], v[18:19], 1.0 op_sel_hi:[1,0]
	v_pk_fma_f32 v[8:9], v[54:55], v[14:15], v[8:9]
	v_pk_fma_f32 v[6:7], v[52:53], v[18:19], v[6:7]
	s_nop 0
	v_cvt_pk_bf16_f32 v6, v6, v7
	v_cvt_pk_bf16_f32 v7, v8, v9
	flat_store_dwordx2 v[10:11], v[6:7] offset:1024
	v_mov_b64_e32 v[6:7], v[194:195]
	v_mov_b64_e32 v[8:9], v[196:197]
	s_nop 0
	v_mov_b64_e32 v[0:1], v[224:225]
	v_mov_b64_e32 v[2:3], v[226:227]
	v_pk_add_f32 v[2:3], v[2:3], 1.0 op_sel_hi:[1,0]
	v_pk_add_f32 v[0:1], v[0:1], 1.0 op_sel_hi:[1,0]
	v_pk_fma_f32 v[2:3], v[50:51], v[2:3], v[8:9]
	v_pk_fma_f32 v[0:1], v[48:49], v[0:1], v[6:7]
	s_nop 0
	v_cvt_pk_bf16_f32 v0, v0, v1
	v_cvt_pk_bf16_f32 v1, v2, v3
	flat_store_dwordx2 v[10:11], v[0:1] offset:1536
	v_lshl_add_u64 v[0:1], v[88:89], 0, s[2:3]
	v_mad_u64_u32 v[2:3], s[4:5], v0, s7, v[94:95]
	v_mad_i32_i24 v3, v1, s7, v3
	v_lshl_add_u64 v[0:1], v[2:3], 0, s[30:31]
	v_lshl_add_u64 v[2:3], v[2:3], 0, v[152:153]
	v_lshl_add_u64 v[10:11], v[0:1], 0, v[152:153]
	global_load_dwordx4 v[186:189], v[2:3], off offset:1024
	global_load_dwordx4 v[190:193], v[2:3], off offset:2048
	global_load_dwordx4 v[194:197], v[2:3], off offset:3072
	flat_load_dwordx4 v[6:9], v[2:3]
	global_load_dwordx4 v[198:201], v[10:11], off offset:1024
	global_load_dwordx4 v[202:205], v[10:11], off offset:2048
	global_load_dwordx4 v[224:227], v[10:11], off offset:3072
	flat_load_dwordx4 v[18:21], v[10:11]
	s_waitcnt vmcnt(0) lgkmcnt(0)
	v_pk_add_f32 v[10:11], v[20:21], 1.0 op_sel_hi:[1,0]
	v_pk_add_f32 v[14:15], v[18:19], 1.0 op_sel_hi:[1,0]
	v_pk_fma_f32 v[8:9], v[46:47], v[10:11], v[8:9]
	v_pk_fma_f32 v[6:7], v[44:45], v[14:15], v[6:7]
	v_lshl_add_u64 v[18:19], v[82:83], 0, v[98:99]
	v_cvt_pk_bf16_f32 v6, v6, v7
	v_cvt_pk_bf16_f32 v7, v8, v9
	flat_store_dwordx2 v[18:19], v[6:7]
	v_lshl_add_u64 v[10:11], v[0:1], 0, v[16:17]
	v_mov_b64_e32 v[6:7], v[186:187]
	v_mov_b64_e32 v[8:9], v[188:189]
	v_mov_b64_e32 v[14:15], v[198:199]
	v_mov_b64_e32 v[16:17], v[200:201]
	v_pk_add_f32 v[10:11], v[16:17], 1.0 op_sel_hi:[1,0]
	v_pk_add_f32 v[14:15], v[14:15], 1.0 op_sel_hi:[1,0]
	v_pk_fma_f32 v[8:9], v[42:43], v[10:11], v[8:9]
	v_pk_fma_f32 v[6:7], v[40:41], v[14:15], v[6:7]
	v_lshl_add_u64 v[10:11], v[0:1], 0, v[12:13]
	v_cvt_pk_bf16_f32 v6, v6, v7
	v_cvt_pk_bf16_f32 v7, v8, v9
	flat_store_dwordx2 v[18:19], v[6:7] offset:512
	v_mov_b64_e32 v[6:7], v[190:191]
	v_mov_b64_e32 v[8:9], v[192:193]
	v_lshl_add_u64 v[0:1], v[0:1], 0, v[4:5]
	v_mov_b64_e32 v[10:11], v[202:203]
	v_mov_b64_e32 v[12:13], v[204:205]
	v_pk_add_f32 v[12:13], v[12:13], 1.0 op_sel_hi:[1,0]
	v_pk_add_f32 v[10:11], v[10:11], 1.0 op_sel_hi:[1,0]
	v_pk_fma_f32 v[8:9], v[38:39], v[12:13], v[8:9]
	v_pk_fma_f32 v[6:7], v[36:37], v[10:11], v[6:7]
	s_nop 0
	v_cvt_pk_bf16_f32 v6, v6, v7
	v_cvt_pk_bf16_f32 v7, v8, v9
	flat_store_dwordx2 v[18:19], v[6:7] offset:1024
	v_mov_b64_e32 v[6:7], v[194:195]
	v_mov_b64_e32 v[8:9], v[196:197]
	s_nop 0
	v_mov_b64_e32 v[0:1], v[224:225]
	v_mov_b64_e32 v[2:3], v[226:227]
	v_pk_add_f32 v[2:3], v[2:3], 1.0 op_sel_hi:[1,0]
	v_pk_add_f32 v[0:1], v[0:1], 1.0 op_sel_hi:[1,0]
	v_pk_fma_f32 v[2:3], v[34:35], v[2:3], v[8:9]
	v_pk_fma_f32 v[0:1], v[32:33], v[0:1], v[6:7]
	s_nop 0
	v_cvt_pk_bf16_f32 v0, v0, v1
	v_cvt_pk_bf16_f32 v1, v2, v3
	flat_store_dwordx2 v[18:19], v[0:1] offset:1536
	s_branch .LBB0_224
